# kk_inner_mfma_order
# speedup vs baseline: 1.0240x; 1.0059x over previous
; #define PG8_STAGE(bufoff, gbase, voff) do { _Pragma("unroll") for (int _i = 0; _i < 2; ++_i) \
;         __builtin_amdgcn_global_load_lds((const unsigned*)((const char*)(gbase) + (voff)[_i]), (PG8_LAS unsigned*)(lds + (bufoff) + ldsw + _i * 8192), 16, 0, 0); } while (0)
; #define PG8_LDA(dst, b, h) do { _Pragma("unroll") for (int m = 0; m < 4; ++m) _Pragma("unroll") for (int k = 0; k < 2; ++k) dst[m][k] = *(const PG8_LAS bf16x8*)(lds + PG8_SA(b, h) + aoff + m * 2048 + k * 1024); } while (0)
; #define PG8_LDB(dst, b, h) do { _Pragma("unroll") for (int n = 0; n < 2; ++n) _Pragma("unroll") for (int k = 0; k < 2; ++k) dst[n][k] = *(const PG8_LAS bf16x8*)(lds + PG8_SB(b, h) + boff + n * 2048 + k * 1024); } while (0)
; template <class Epi, class Sched, bool ALIGN_EPI = false, bool SP2 = false>
; __device__ __forceinline__ void gemm_phase(PG8_LAS unsigned char* lds, const Gemm g, const Sched& S, const Epi& E) {
;     ...
;         for (int t = 0; t < nt; t += 2) {
;             const bool last = (t == nt - 2);
;             const char* a1 = cA + (size_t)(t + 1) * kstep;
;             const char* a2 = last ? nA : cA + (size_t)(t + 2) * kstep; const char* b2 = last ? nB : cB + (size_t)(t + 2) * kstep;
;             const char* a3 = a2 + kstep; const char* b3 = b2 + kstep;
;             if (last && has_next) S.a_ready(nxt);
;             if constexpr (SP2) {
;             PG8_LDB(B0, 0, 0); PG8_LDB(B1, 0, 1); PG8_SCHED; PG8_LDA(At, 0, 0); PG8_STAGE(PG8_SA(1, 1), a1 + hstep, voffA);
;             PG8_WAIT_V(8); PG8_WAIT_L(0); PG8_BAR; PG8_MMA(0, 0, At, B0); PG8_MMA(0, 1, At, B1); PG8_BAR; PG8_SCHED;
;             PG8_LDA(At, 0, 1); PG8_STAGE(PG8_SB(0, 0), b2, voffB); PG8_STAGE(PG8_SB(0, 1), b2 + hstep, voffB); PG8_STAGE(PG8_SA(0, 0), a2, voffA);
;             PG8_WAIT_V(8); PG8_WAIT_L(0); PG8_BAR; PG8_MMA(1, 0, At, B0); PG8_MMA(1, 1, At, B1); PG8_BAR; PG8_SCHED;
;             PG8_LDB(B0, 1, 0); PG8_LDB(B1, 1, 1); PG8_SCHED; PG8_LDA(At, 1, 0); PG8_STAGE(PG8_SA(0, 1), a2 + hstep, voffA);
;             PG8_WAIT_V(8); PG8_WAIT_L(0); PG8_BAR; PG8_MMA(0, 0, At, B0); PG8_MMA(0, 1, At, B1); PG8_BAR; PG8_SCHED;
;             PG8_LDA(At, 1, 1); PG8_STAGE(PG8_SB(1, 0), b3, voffB); PG8_STAGE(PG8_SB(1, 1), b3 + hstep, voffB); PG8_STAGE(PG8_SA(1, 0), a3, voffA);
;             PG8_WAIT_V(8); PG8_WAIT_L(0); PG8_BAR; PG8_MMA(1, 0, At, B0); PG8_MMA(1, 1, At, B1); PG8_BAR; PG8_SCHED;
.Lp5_kloop0:
	s_waitcnt vmcnt(8)
	s_waitcnt lgkmcnt(0)
	s_barrier
	v_mfma_f32_16x16x32_bf16 v[0:3], v[194:197], v[128:131], v[0:3]
	ds_read_b128 v[210:213], v247 offset:16384
	v_mfma_f32_16x16x32_bf16 v[0:3], v[198:201], v[132:135], v[0:3]
	ds_read_b128 v[214:217], v248 offset:16384
	v_mfma_f32_16x16x32_bf16 v[4:7], v[202:205], v[128:131], v[4:7]
	ds_read_b128 v[218:221], v247 offset:18432
	v_mfma_f32_16x16x32_bf16 v[4:7], v[206:209], v[132:135], v[4:7]
	ds_read_b128 v[222:225], v248 offset:18432
	v_mfma_f32_16x16x32_bf16 v[8:11], v[194:197], v[136:139], v[8:11]
	s_add_i32 m0, s35, 0x0
	v_mfma_f32_16x16x32_bf16 v[8:11], v[198:201], v[140:143], v[8:11]
	global_load_lds_dwordx4 v249, s[30:31]
	v_mfma_f32_16x16x32_bf16 v[12:15], v[202:205], v[136:139], v[12:15]
	s_add_i32 m0, s35, 0x2000
	v_mfma_f32_16x16x32_bf16 v[12:15], v[206:209], v[140:143], v[12:15]
	global_load_lds_dwordx4 v250, s[30:31]
	v_mfma_f32_16x16x32_bf16 v[16:19], v[194:197], v[144:147], v[16:19]
	s_add_i32 m0, s35, 0x10000
	v_mfma_f32_16x16x32_bf16 v[16:19], v[198:201], v[148:151], v[16:19]
	global_load_lds_dwordx4 v251, s[32:33]
	v_mfma_f32_16x16x32_bf16 v[20:23], v[202:205], v[144:147], v[20:23]
	s_add_i32 m0, s35, 0x12000
	v_mfma_f32_16x16x32_bf16 v[20:23], v[206:209], v[148:151], v[20:23]
	global_load_lds_dwordx4 v252, s[32:33]
	v_mfma_f32_16x16x32_bf16 v[24:27], v[194:197], v[152:155], v[24:27]
	ds_read_b128 v[160:163], v245 offset:16384
	v_mfma_f32_16x16x32_bf16 v[24:27], v[198:201], v[156:159], v[24:27]
	ds_read_b128 v[164:167], v246 offset:16384
	v_mfma_f32_16x16x32_bf16 v[28:31], v[202:205], v[152:155], v[28:31]
	ds_read_b128 v[168:171], v245 offset:18432
	v_mfma_f32_16x16x32_bf16 v[28:31], v[206:209], v[156:159], v[28:31]
	ds_read_b128 v[172:175], v246 offset:18432
	s_waitcnt lgkmcnt(4)
	v_mfma_f32_16x16x32_bf16 v[32:35], v[210:213], v[128:131], v[32:35]
	ds_read_b128 v[176:179], v245 offset:20480
	v_mfma_f32_16x16x32_bf16 v[32:35], v[214:217], v[132:135], v[32:35]
	ds_read_b128 v[180:183], v246 offset:20480
	v_mfma_f32_16x16x32_bf16 v[36:39], v[218:221], v[128:131], v[36:39]
	ds_read_b128 v[186:189], v245 offset:22528
	v_mfma_f32_16x16x32_bf16 v[36:39], v[222:225], v[132:135], v[36:39]
	ds_read_b128 v[190:193], v246 offset:22528
	v_mfma_f32_16x16x32_bf16 v[40:43], v[210:213], v[136:139], v[40:43]
	v_mfma_f32_16x16x32_bf16 v[40:43], v[214:217], v[140:143], v[40:43]
	v_mfma_f32_16x16x32_bf16 v[44:47], v[218:221], v[136:139], v[44:47]
	v_mfma_f32_16x16x32_bf16 v[44:47], v[222:225], v[140:143], v[44:47]
	v_mfma_f32_16x16x32_bf16 v[48:51], v[210:213], v[144:147], v[48:51]
	v_mfma_f32_16x16x32_bf16 v[48:51], v[214:217], v[148:151], v[48:51]
	v_mfma_f32_16x16x32_bf16 v[52:55], v[218:221], v[144:147], v[52:55]
	v_mfma_f32_16x16x32_bf16 v[52:55], v[222:225], v[148:151], v[52:55]
	v_mfma_f32_16x16x32_bf16 v[56:59], v[210:213], v[152:155], v[56:59]
	v_mfma_f32_16x16x32_bf16 v[56:59], v[214:217], v[156:159], v[56:59]
	v_mfma_f32_16x16x32_bf16 v[60:63], v[218:221], v[152:155], v[60:63]
	v_mfma_f32_16x16x32_bf16 v[60:63], v[222:225], v[156:159], v[60:63]
	s_waitcnt vmcnt(8)
	s_waitcnt lgkmcnt(0)
	s_barrier
	v_mfma_f32_16x16x32_bf16 v[96:99], v[210:213], v[160:163], v[96:99]
	s_add_i32 m0, s35, 0x4000
	v_mfma_f32_16x16x32_bf16 v[96:99], v[214:217], v[164:167], v[96:99]
	global_load_lds_dwordx4 v249, s[56:57]
	v_mfma_f32_16x16x32_bf16 v[100:103], v[218:221], v[160:163], v[100:103]
	s_add_i32 m0, s35, 0x6000
	v_mfma_f32_16x16x32_bf16 v[100:103], v[222:225], v[164:167], v[100:103]
	global_load_lds_dwordx4 v250, s[56:57]
	v_mfma_f32_16x16x32_bf16 v[104:107], v[210:213], v[168:171], v[104:107]
	s_add_i32 m0, s35, 0x14000
	v_mfma_f32_16x16x32_bf16 v[104:107], v[214:217], v[172:175], v[104:107]
	global_load_lds_dwordx4 v251, s[58:59]
	v_mfma_f32_16x16x32_bf16 v[108:111], v[218:221], v[168:171], v[108:111]
	s_add_i32 m0, s35, 0x16000
	v_mfma_f32_16x16x32_bf16 v[108:111], v[222:225], v[172:175], v[108:111]
	global_load_lds_dwordx4 v252, s[58:59]
	v_mfma_f32_16x16x32_bf16 v[112:115], v[210:213], v[176:179], v[112:115]
	ds_read_b128 v[128:131], v245 offset:32768
	v_mfma_f32_16x16x32_bf16 v[112:115], v[214:217], v[180:183], v[112:115]
	ds_read_b128 v[132:135], v246 offset:32768
	v_mfma_f32_16x16x32_bf16 v[116:119], v[218:221], v[176:179], v[116:119]
	ds_read_b128 v[136:139], v245 offset:34816
	v_mfma_f32_16x16x32_bf16 v[116:119], v[222:225], v[180:183], v[116:119]
	ds_read_b128 v[140:143], v246 offset:34816
	v_mfma_f32_16x16x32_bf16 v[120:123], v[210:213], v[186:189], v[120:123]
	ds_read_b128 v[144:147], v245 offset:36864
	v_mfma_f32_16x16x32_bf16 v[120:123], v[214:217], v[190:193], v[120:123]
	ds_read_b128 v[148:151], v246 offset:36864
	v_mfma_f32_16x16x32_bf16 v[124:127], v[218:221], v[186:189], v[124:127]
	ds_read_b128 v[152:155], v245 offset:38912
	v_mfma_f32_16x16x32_bf16 v[124:127], v[222:225], v[190:193], v[124:127]
	ds_read_b128 v[156:159], v246 offset:38912
	v_mfma_f32_16x16x32_bf16 v[64:67], v[194:197], v[160:163], v[64:67]
	ds_read_b128 v[210:213], v247 offset:49152
	v_mfma_f32_16x16x32_bf16 v[64:67], v[198:201], v[164:167], v[64:67]
	ds_read_b128 v[214:217], v248 offset:49152
	v_mfma_f32_16x16x32_bf16 v[68:71], v[202:205], v[160:163], v[68:71]
	ds_read_b128 v[218:221], v247 offset:51200
	v_mfma_f32_16x16x32_bf16 v[68:71], v[206:209], v[164:167], v[68:71]
	ds_read_b128 v[222:225], v248 offset:51200
	v_mfma_f32_16x16x32_bf16 v[72:75], v[194:197], v[168:171], v[72:75]
	s_add_u32 s30, s30, s4
	s_addc_u32 s31, s31, s5
	v_mfma_f32_16x16x32_bf16 v[72:75], v[198:201], v[172:175], v[72:75]
	s_add_u32 s56, s56, s4
	s_addc_u32 s57, s57, s5
	v_mfma_f32_16x16x32_bf16 v[76:79], v[202:205], v[168:171], v[76:79]
	s_add_u32 s32, s32, s4
	s_addc_u32 s33, s33, s5
	v_mfma_f32_16x16x32_bf16 v[76:79], v[206:209], v[172:175], v[76:79]
	s_add_u32 s58, s58, s4
	s_addc_u32 s59, s59, s5
	v_mfma_f32_16x16x32_bf16 v[80:83], v[194:197], v[176:179], v[80:83]
	v_mfma_f32_16x16x32_bf16 v[80:83], v[198:201], v[180:183], v[80:83]
	v_mfma_f32_16x16x32_bf16 v[84:87], v[202:205], v[176:179], v[84:87]
	v_mfma_f32_16x16x32_bf16 v[84:87], v[206:209], v[180:183], v[84:87]
	v_mfma_f32_16x16x32_bf16 v[88:91], v[194:197], v[186:189], v[88:91]
	v_mfma_f32_16x16x32_bf16 v[88:91], v[198:201], v[190:193], v[88:91]
	v_mfma_f32_16x16x32_bf16 v[92:95], v[202:205], v[186:189], v[92:95]
	v_mfma_f32_16x16x32_bf16 v[92:95], v[206:209], v[190:193], v[92:95]
	s_waitcnt vmcnt(8)
	s_waitcnt lgkmcnt(0)
	s_barrier
; #define PG8_STAGE(bufoff, gbase, voff) do { _Pragma("unroll") for (int _i = 0; _i < 2; ++_i) \
;         __builtin_amdgcn_global_load_lds((const unsigned*)((const char*)(gbase) + (voff)[_i]), (PG8_LAS unsigned*)(lds + (bufoff) + ldsw + _i * 8192), 16, 0, 0); } while (0)
; #define PG8_LDA(dst, b, h) do { _Pragma("unroll") for (int m = 0; m < 4; ++m) _Pragma("unroll") for (int k = 0; k < 2; ++k) dst[m][k] = *(const PG8_LAS bf16x8*)(lds + PG8_SA(b, h) + aoff + m * 2048 + k * 1024); } while (0)
; template <class Epi, class Sched, bool ALIGN_EPI = false, bool SP2 = false>
; __device__ __forceinline__ void gemm_phase(PG8_LAS unsigned char* lds, const Gemm g, const Sched& S, const Epi& E) {
;     ...
;         const bool has_next = S.next(ui + 1, nxt);
;         const char* nA = has_next ? (const char*)g.A + (size_t)nxt.pm * tstep : cA; const char* nB = has_next ? (const char*)g.Bt + (size_t)nxt.pn * tstep : cB;
;         for (int t = 0; t < nt; t += 2) {
;             const bool last = (t == nt - 2);
;             const char* a1 = cA + (size_t)(t + 1) * kstep;
;             const char* a2 = last ? nA : cA + (size_t)(t + 2) * kstep; const char* b2 = last ? nB : cB + (size_t)(t + 2) * kstep;
;             const char* a3 = a2 + kstep; const char* b3 = b2 + kstep;
;             if (last && has_next) S.a_ready(nxt);
;             if constexpr (SP2) {
;             PG8_LDB(B0, 0, 0); PG8_LDB(B1, 0, 1); PG8_SCHED; PG8_LDA(At, 0, 0); PG8_STAGE(PG8_SA(1, 1), a1 + hstep, voffA);
;             PG8_WAIT_V(8); PG8_WAIT_L(0); PG8_BAR; PG8_MMA(0, 0, At, B0); PG8_MMA(0, 1, At, B1); PG8_BAR; PG8_SCHED;
;             PG8_LDA(At, 0, 1); PG8_STAGE(PG8_SB(0, 0), b2, voffB); PG8_STAGE(PG8_SB(0, 1), b2 + hstep, voffB); PG8_STAGE(PG8_SA(0, 0), a2, voffA);
;             PG8_WAIT_V(8); PG8_WAIT_L(0); PG8_BAR; PG8_MMA(1, 0, At, B0); PG8_MMA(1, 1, At, B1); PG8_BAR; PG8_SCHED;
;             PG8_LDB(B0, 1, 0); PG8_LDB(B1, 1, 1); PG8_SCHED; PG8_LDA(At, 1, 0); PG8_STAGE(PG8_SA(0, 1), a2 + hstep, voffA);
;             PG8_WAIT_V(8); PG8_WAIT_L(0); PG8_BAR; PG8_MMA(0, 0, At, B0); PG8_MMA(0, 1, At, B1); PG8_BAR; PG8_SCHED;
;             PG8_LDA(At, 1, 1); PG8_STAGE(PG8_SB(1, 0), b3, voffB); PG8_STAGE(PG8_SB(1, 1), b3 + hstep, voffB); PG8_STAGE(PG8_SA(1, 0), a3, voffA);
;             PG8_WAIT_V(8); PG8_WAIT_L(0); PG8_BAR; PG8_MMA(1, 0, At, B0); PG8_MMA(1, 1, At, B1); PG8_BAR; PG8_SCHED;
	v_mfma_f32_16x16x32_bf16 v[32:35], v[210:213], v[128:131], v[32:35]
	ds_read_b128 v[194:197], v247 offset:32768
	v_mfma_f32_16x16x32_bf16 v[32:35], v[214:217], v[132:135], v[32:35]
	ds_read_b128 v[198:201], v248 offset:32768
	v_mfma_f32_16x16x32_bf16 v[36:39], v[218:221], v[128:131], v[36:39]
	ds_read_b128 v[202:205], v247 offset:34816
	v_mfma_f32_16x16x32_bf16 v[36:39], v[222:225], v[132:135], v[36:39]
	ds_read_b128 v[206:209], v248 offset:34816
	v_mfma_f32_16x16x32_bf16 v[40:43], v[210:213], v[136:139], v[40:43]
	s_add_i32 m0, s35, 0x8000
	v_mfma_f32_16x16x32_bf16 v[40:43], v[214:217], v[140:143], v[40:43]
	global_load_lds_dwordx4 v249, s[30:31]
	v_mfma_f32_16x16x32_bf16 v[44:47], v[218:221], v[136:139], v[44:47]
	s_add_i32 m0, s35, 0xa000
	v_mfma_f32_16x16x32_bf16 v[44:47], v[222:225], v[140:143], v[44:47]
	global_load_lds_dwordx4 v250, s[30:31]
	v_mfma_f32_16x16x32_bf16 v[48:51], v[210:213], v[144:147], v[48:51]
	s_add_i32 m0, s35, 0x1c000
	v_mfma_f32_16x16x32_bf16 v[48:51], v[214:217], v[148:151], v[48:51]
	global_load_lds_dwordx4 v251, s[58:59]
	v_mfma_f32_16x16x32_bf16 v[52:55], v[218:221], v[144:147], v[52:55]
	s_add_i32 m0, s35, 0x1e000
	v_mfma_f32_16x16x32_bf16 v[52:55], v[222:225], v[148:151], v[52:55]
	global_load_lds_dwordx4 v252, s[58:59]
	v_mfma_f32_16x16x32_bf16 v[56:59], v[210:213], v[152:155], v[56:59]
	ds_read_b128 v[160:163], v245 offset:49152
	v_mfma_f32_16x16x32_bf16 v[56:59], v[214:217], v[156:159], v[56:59]
	ds_read_b128 v[164:167], v246 offset:49152
	v_mfma_f32_16x16x32_bf16 v[60:63], v[218:221], v[152:155], v[60:63]
	ds_read_b128 v[168:171], v245 offset:51200
	v_mfma_f32_16x16x32_bf16 v[60:63], v[222:225], v[156:159], v[60:63]
	ds_read_b128 v[172:175], v246 offset:51200
	s_waitcnt lgkmcnt(4)
	v_mfma_f32_16x16x32_bf16 v[0:3], v[194:197], v[128:131], v[0:3]
	ds_read_b128 v[176:179], v245 offset:53248
	v_mfma_f32_16x16x32_bf16 v[0:3], v[198:201], v[132:135], v[0:3]
	ds_read_b128 v[180:183], v246 offset:53248
	v_mfma_f32_16x16x32_bf16 v[4:7], v[202:205], v[128:131], v[4:7]
	ds_read_b128 v[186:189], v245 offset:55296
	v_mfma_f32_16x16x32_bf16 v[4:7], v[206:209], v[132:135], v[4:7]
	ds_read_b128 v[190:193], v246 offset:55296
	v_mfma_f32_16x16x32_bf16 v[8:11], v[194:197], v[136:139], v[8:11]
	v_mfma_f32_16x16x32_bf16 v[8:11], v[198:201], v[140:143], v[8:11]
	v_mfma_f32_16x16x32_bf16 v[12:15], v[202:205], v[136:139], v[12:15]
	v_mfma_f32_16x16x32_bf16 v[12:15], v[206:209], v[140:143], v[12:15]
	v_mfma_f32_16x16x32_bf16 v[16:19], v[194:197], v[144:147], v[16:19]
	v_mfma_f32_16x16x32_bf16 v[16:19], v[198:201], v[148:151], v[16:19]
	v_mfma_f32_16x16x32_bf16 v[20:23], v[202:205], v[144:147], v[20:23]
	v_mfma_f32_16x16x32_bf16 v[20:23], v[206:209], v[148:151], v[20:23]
	v_mfma_f32_16x16x32_bf16 v[24:27], v[194:197], v[152:155], v[24:27]
	v_mfma_f32_16x16x32_bf16 v[24:27], v[198:201], v[156:159], v[24:27]
	v_mfma_f32_16x16x32_bf16 v[28:31], v[202:205], v[152:155], v[28:31]
	v_mfma_f32_16x16x32_bf16 v[28:31], v[206:209], v[156:159], v[28:31]
	s_waitcnt vmcnt(8)
	s_waitcnt lgkmcnt(0)
	s_barrier
	v_mfma_f32_16x16x32_bf16 v[64:67], v[194:197], v[160:163], v[64:67]
	s_add_i32 m0, s35, 0xc000
	v_mfma_f32_16x16x32_bf16 v[64:67], v[198:201], v[164:167], v[64:67]
	global_load_lds_dwordx4 v249, s[56:57]
	v_mfma_f32_16x16x32_bf16 v[68:71], v[202:205], v[160:163], v[68:71]
	s_add_i32 m0, s35, 0xe000
	v_mfma_f32_16x16x32_bf16 v[68:71], v[206:209], v[164:167], v[68:71]
	global_load_lds_dwordx4 v250, s[56:57]
	v_mfma_f32_16x16x32_bf16 v[72:75], v[194:197], v[168:171], v[72:75]
	s_add_i32 m0, s35, 0x18000
	v_mfma_f32_16x16x32_bf16 v[72:75], v[198:201], v[172:175], v[72:75]
	global_load_lds_dwordx4 v251, s[32:33]
	v_mfma_f32_16x16x32_bf16 v[76:79], v[202:205], v[168:171], v[76:79]
	s_add_i32 m0, s35, 0x1a000
	v_mfma_f32_16x16x32_bf16 v[76:79], v[206:209], v[172:175], v[76:79]
	global_load_lds_dwordx4 v252, s[32:33]
	v_mfma_f32_16x16x32_bf16 v[80:83], v[194:197], v[176:179], v[80:83]
	ds_read_b128 v[128:131], v245 offset:0
	v_mfma_f32_16x16x32_bf16 v[80:83], v[198:201], v[180:183], v[80:83]
	ds_read_b128 v[132:135], v246 offset:0
	v_mfma_f32_16x16x32_bf16 v[84:87], v[202:205], v[176:179], v[84:87]
	ds_read_b128 v[136:139], v245 offset:2048
	v_mfma_f32_16x16x32_bf16 v[84:87], v[206:209], v[180:183], v[84:87]
	ds_read_b128 v[140:143], v246 offset:2048
	v_mfma_f32_16x16x32_bf16 v[88:91], v[194:197], v[186:189], v[88:91]
	ds_read_b128 v[144:147], v245 offset:4096
	v_mfma_f32_16x16x32_bf16 v[88:91], v[198:201], v[190:193], v[88:91]
	ds_read_b128 v[148:151], v246 offset:4096
	v_mfma_f32_16x16x32_bf16 v[92:95], v[202:205], v[186:189], v[92:95]
	ds_read_b128 v[152:155], v245 offset:6144
	v_mfma_f32_16x16x32_bf16 v[92:95], v[206:209], v[190:193], v[92:95]
	ds_read_b128 v[156:159], v246 offset:6144
	v_mfma_f32_16x16x32_bf16 v[96:99], v[210:213], v[160:163], v[96:99]
	ds_read_b128 v[194:197], v247 offset:0
	v_mfma_f32_16x16x32_bf16 v[96:99], v[214:217], v[164:167], v[96:99]
	ds_read_b128 v[198:201], v248 offset:0
	v_mfma_f32_16x16x32_bf16 v[100:103], v[218:221], v[160:163], v[100:103]
	ds_read_b128 v[202:205], v247 offset:2048
	v_mfma_f32_16x16x32_bf16 v[100:103], v[222:225], v[164:167], v[100:103]
	ds_read_b128 v[206:209], v248 offset:2048
	v_mfma_f32_16x16x32_bf16 v[104:107], v[210:213], v[168:171], v[104:107]
	s_add_u32 s30, s30, s4
	s_addc_u32 s31, s31, s5
	v_mfma_f32_16x16x32_bf16 v[104:107], v[214:217], v[172:175], v[104:107]
	s_add_u32 s56, s56, s4
	s_addc_u32 s57, s57, s5
	v_mfma_f32_16x16x32_bf16 v[108:111], v[218:221], v[168:171], v[108:111]
	s_add_u32 s32, s32, s4
	s_addc_u32 s33, s33, s5
	v_mfma_f32_16x16x32_bf16 v[108:111], v[222:225], v[172:175], v[108:111]
	s_add_u32 s58, s58, s4
	s_addc_u32 s59, s59, s5
	v_mfma_f32_16x16x32_bf16 v[112:115], v[210:213], v[176:179], v[112:115]
	v_mfma_f32_16x16x32_bf16 v[112:115], v[214:217], v[180:183], v[112:115]
	v_mfma_f32_16x16x32_bf16 v[116:119], v[218:221], v[176:179], v[116:119]
	v_mfma_f32_16x16x32_bf16 v[116:119], v[222:225], v[180:183], v[116:119]
	v_mfma_f32_16x16x32_bf16 v[120:123], v[210:213], v[186:189], v[120:123]
	v_mfma_f32_16x16x32_bf16 v[120:123], v[214:217], v[190:193], v[120:123]
	v_mfma_f32_16x16x32_bf16 v[124:127], v[218:221], v[186:189], v[124:127]
	v_mfma_f32_16x16x32_bf16 v[124:127], v[222:225], v[190:193], v[124:127]
	s_add_i32 s34, s34, -1
	s_cmp_lg_u32 s34, 1
	s_cbranch_scc1 .Lp5_nosw0
	s_add_u32 s45, s16, 1
	s_and_b32 s40, s45, 1
	s_lshl_b32 s4, s40, 8
	s_sub_u32 s4, 128, s4
	s_sub_u32 s5, 0, s40
	s_mul_i32 s8, s40, 3968
	s_add_u32 s30, s26, s8
	s_addc_u32 s31, s27, 0
	s_add_u32 s32, s28, s8
	s_addc_u32 s33, s29, 0
	s_add_u32 s56, s30, 0x80000
	s_addc_u32 s57, s31, 0
	s_add_u32 s58, s32, 0x80000
	s_addc_u32 s59, s33, 0

; #define PG8_STAGE(bufoff, gbase, voff) do { _Pragma("unroll") for (int _i = 0; _i < 2; ++_i) \
;         __builtin_amdgcn_global_load_lds((const unsigned*)((const char*)(gbase) + (voff)[_i]), (PG8_LAS unsigned*)(lds + (bufoff) + ldsw + _i * 8192), 16, 0, 0); } while (0)
; #define PG8_LDA(dst, b, h) do { _Pragma("unroll") for (int m = 0; m < 4; ++m) _Pragma("unroll") for (int k = 0; k < 2; ++k) dst[m][k] = *(const PG8_LAS bf16x8*)(lds + PG8_SA(b, h) + aoff + m * 2048 + k * 1024); } while (0)
; #define PG8_LDB(dst, b, h) do { _Pragma("unroll") for (int n = 0; n < 2; ++n) _Pragma("unroll") for (int k = 0; k < 2; ++k) dst[n][k] = *(const PG8_LAS bf16x8*)(lds + PG8_SB(b, h) + boff + n * 2048 + k * 1024); } while (0)
; template <class Epi, class Sched, bool ALIGN_EPI = false, bool SP2 = false>
; __device__ __forceinline__ void gemm_phase(PG8_LAS unsigned char* lds, const Gemm g, const Sched& S, const Epi& E) {
;     ...
;         for (int t = 0; t < nt; t += 2) {
;             const bool last = (t == nt - 2);
;             const char* a1 = cA + (size_t)(t + 1) * kstep;
;             const char* a2 = last ? nA : cA + (size_t)(t + 2) * kstep; const char* b2 = last ? nB : cB + (size_t)(t + 2) * kstep;
;             const char* a3 = a2 + kstep; const char* b3 = b2 + kstep;
;             if (last && has_next) S.a_ready(nxt);
;             if constexpr (SP2) {
;             PG8_LDB(B0, 0, 0); PG8_LDB(B1, 0, 1); PG8_SCHED; PG8_LDA(At, 0, 0); PG8_STAGE(PG8_SA(1, 1), a1 + hstep, voffA);
;             PG8_WAIT_V(8); PG8_WAIT_L(0); PG8_BAR; PG8_MMA(0, 0, At, B0); PG8_MMA(0, 1, At, B1); PG8_BAR; PG8_SCHED;
;             PG8_LDA(At, 0, 1); PG8_STAGE(PG8_SB(0, 0), b2, voffB); PG8_STAGE(PG8_SB(0, 1), b2 + hstep, voffB); PG8_STAGE(PG8_SA(0, 0), a2, voffA);
;             PG8_WAIT_V(8); PG8_WAIT_L(0); PG8_BAR; PG8_MMA(1, 0, At, B0); PG8_MMA(1, 1, At, B1); PG8_BAR; PG8_SCHED;
;             PG8_LDB(B0, 1, 0); PG8_LDB(B1, 1, 1); PG8_SCHED; PG8_LDA(At, 1, 0); PG8_STAGE(PG8_SA(0, 1), a2 + hstep, voffA);
;             PG8_WAIT_V(8); PG8_WAIT_L(0); PG8_BAR; PG8_MMA(0, 0, At, B0); PG8_MMA(0, 1, At, B1); PG8_BAR; PG8_SCHED;
;             PG8_LDA(At, 1, 1); PG8_STAGE(PG8_SB(1, 0), b3, voffB); PG8_STAGE(PG8_SB(1, 1), b3 + hstep, voffB); PG8_STAGE(PG8_SA(1, 0), a3, voffA);
;             PG8_WAIT_V(8); PG8_WAIT_L(0); PG8_BAR; PG8_MMA(1, 0, At, B0); PG8_MMA(1, 1, At, B1); PG8_BAR; PG8_SCHED;
.Lp5_kloop1:
	s_waitcnt vmcnt(8)
	s_waitcnt lgkmcnt(0)
	s_barrier
	v_mfma_f32_16x16x32_bf16 v[0:3], v[194:197], v[128:131], v[0:3]
	ds_read_b128 v[210:213], v247 offset:16384
	v_mfma_f32_16x16x32_bf16 v[0:3], v[198:201], v[132:135], v[0:3]
	ds_read_b128 v[214:217], v248 offset:16384
	v_mfma_f32_16x16x32_bf16 v[4:7], v[202:205], v[128:131], v[4:7]
	ds_read_b128 v[218:221], v247 offset:18432
	v_mfma_f32_16x16x32_bf16 v[4:7], v[206:209], v[132:135], v[4:7]
	ds_read_b128 v[222:225], v248 offset:18432
	v_mfma_f32_16x16x32_bf16 v[8:11], v[194:197], v[136:139], v[8:11]
	ds_read_b128 v[160:163], v245 offset:16384
	v_mfma_f32_16x16x32_bf16 v[8:11], v[198:201], v[140:143], v[8:11]
	ds_read_b128 v[164:167], v246 offset:16384
	v_mfma_f32_16x16x32_bf16 v[12:15], v[202:205], v[136:139], v[12:15]
	ds_read_b128 v[168:171], v245 offset:18432
	v_mfma_f32_16x16x32_bf16 v[12:15], v[206:209], v[140:143], v[12:15]
	ds_read_b128 v[172:175], v246 offset:18432
	v_mfma_f32_16x16x32_bf16 v[16:19], v[194:197], v[144:147], v[16:19]
	ds_read_b128 v[176:179], v245 offset:20480
	v_mfma_f32_16x16x32_bf16 v[16:19], v[198:201], v[148:151], v[16:19]
	ds_read_b128 v[180:183], v246 offset:20480
	v_mfma_f32_16x16x32_bf16 v[20:23], v[202:205], v[144:147], v[20:23]
	ds_read_b128 v[186:189], v245 offset:22528
	v_mfma_f32_16x16x32_bf16 v[20:23], v[206:209], v[148:151], v[20:23]
	ds_read_b128 v[190:193], v246 offset:22528
	v_mfma_f32_16x16x32_bf16 v[24:27], v[194:197], v[152:155], v[24:27]
	v_mfma_f32_16x16x32_bf16 v[24:27], v[198:201], v[156:159], v[24:27]
	v_mfma_f32_16x16x32_bf16 v[28:31], v[202:205], v[152:155], v[28:31]
	v_mfma_f32_16x16x32_bf16 v[28:31], v[206:209], v[156:159], v[28:31]
	s_waitcnt lgkmcnt(8)
	v_mfma_f32_16x16x32_bf16 v[32:35], v[210:213], v[128:131], v[32:35]
	v_mfma_f32_16x16x32_bf16 v[32:35], v[214:217], v[132:135], v[32:35]
	s_add_i32 m0, s35, 0x0
	v_mfma_f32_16x16x32_bf16 v[36:39], v[218:221], v[128:131], v[36:39]
	global_load_lds_dwordx4 v249, s[30:31]
	v_mfma_f32_16x16x32_bf16 v[36:39], v[222:225], v[132:135], v[36:39]
	v_mfma_f32_16x16x32_bf16 v[40:43], v[210:213], v[136:139], v[40:43]
	s_add_i32 m0, s35, 0x2000
	v_mfma_f32_16x16x32_bf16 v[40:43], v[214:217], v[140:143], v[40:43]
	global_load_lds_dwordx4 v250, s[30:31]
	v_mfma_f32_16x16x32_bf16 v[44:47], v[218:221], v[136:139], v[44:47]
	v_mfma_f32_16x16x32_bf16 v[44:47], v[222:225], v[140:143], v[44:47]
	s_add_i32 m0, s35, 0x10000
	v_mfma_f32_16x16x32_bf16 v[48:51], v[210:213], v[144:147], v[48:51]
	global_load_lds_dwordx4 v251, s[32:33]
	v_mfma_f32_16x16x32_bf16 v[48:51], v[214:217], v[148:151], v[48:51]
	v_mfma_f32_16x16x32_bf16 v[52:55], v[218:221], v[144:147], v[52:55]
	s_add_i32 m0, s35, 0x12000
	v_mfma_f32_16x16x32_bf16 v[52:55], v[222:225], v[148:151], v[52:55]
	global_load_lds_dwordx4 v252, s[32:33]
	v_mfma_f32_16x16x32_bf16 v[56:59], v[210:213], v[152:155], v[56:59]
	v_mfma_f32_16x16x32_bf16 v[56:59], v[214:217], v[156:159], v[56:59]
	v_mfma_f32_16x16x32_bf16 v[60:63], v[218:221], v[152:155], v[60:63]
	v_mfma_f32_16x16x32_bf16 v[60:63], v[222:225], v[156:159], v[60:63]
	s_waitcnt vmcnt(8)
	s_waitcnt lgkmcnt(0)
	s_barrier
	v_mfma_f32_16x16x32_bf16 v[96:99], v[210:213], v[160:163], v[96:99]
	ds_read_b128 v[128:131], v245 offset:32768
	v_mfma_f32_16x16x32_bf16 v[96:99], v[214:217], v[164:167], v[96:99]
	ds_read_b128 v[132:135], v246 offset:32768
	v_mfma_f32_16x16x32_bf16 v[100:103], v[218:221], v[160:163], v[100:103]
	ds_read_b128 v[136:139], v245 offset:34816
	v_mfma_f32_16x16x32_bf16 v[100:103], v[222:225], v[164:167], v[100:103]
	ds_read_b128 v[140:143], v246 offset:34816
	v_mfma_f32_16x16x32_bf16 v[104:107], v[210:213], v[168:171], v[104:107]
	ds_read_b128 v[144:147], v245 offset:36864
	v_mfma_f32_16x16x32_bf16 v[104:107], v[214:217], v[172:175], v[104:107]
	ds_read_b128 v[148:151], v246 offset:36864
	v_mfma_f32_16x16x32_bf16 v[108:111], v[218:221], v[168:171], v[108:111]
	ds_read_b128 v[152:155], v245 offset:38912
	v_mfma_f32_16x16x32_bf16 v[108:111], v[222:225], v[172:175], v[108:111]
	ds_read_b128 v[156:159], v246 offset:38912
	v_mfma_f32_16x16x32_bf16 v[112:115], v[210:213], v[176:179], v[112:115]
	v_mfma_f32_16x16x32_bf16 v[112:115], v[214:217], v[180:183], v[112:115]
	v_mfma_f32_16x16x32_bf16 v[116:119], v[218:221], v[176:179], v[116:119]
	v_mfma_f32_16x16x32_bf16 v[116:119], v[222:225], v[180:183], v[116:119]
	v_mfma_f32_16x16x32_bf16 v[120:123], v[210:213], v[186:189], v[120:123]
	v_mfma_f32_16x16x32_bf16 v[120:123], v[214:217], v[190:193], v[120:123]
	v_mfma_f32_16x16x32_bf16 v[124:127], v[218:221], v[186:189], v[124:127]
	v_mfma_f32_16x16x32_bf16 v[124:127], v[222:225], v[190:193], v[124:127]
	v_mfma_f32_16x16x32_bf16 v[64:67], v[194:197], v[160:163], v[64:67]
	ds_read_b128 v[210:213], v247 offset:49152
	v_mfma_f32_16x16x32_bf16 v[64:67], v[198:201], v[164:167], v[64:67]
	ds_read_b128 v[214:217], v248 offset:49152
	v_mfma_f32_16x16x32_bf16 v[68:71], v[202:205], v[160:163], v[68:71]
	ds_read_b128 v[218:221], v247 offset:51200
	v_mfma_f32_16x16x32_bf16 v[68:71], v[206:209], v[164:167], v[68:71]
	ds_read_b128 v[222:225], v248 offset:51200
	v_mfma_f32_16x16x32_bf16 v[72:75], v[194:197], v[168:171], v[72:75]
	s_add_i32 m0, s35, 0x4000
	v_mfma_f32_16x16x32_bf16 v[72:75], v[198:201], v[172:175], v[72:75]
	global_load_lds_dwordx4 v249, s[56:57]
	v_mfma_f32_16x16x32_bf16 v[76:79], v[202:205], v[168:171], v[76:79]
	s_add_i32 m0, s35, 0x6000
	v_mfma_f32_16x16x32_bf16 v[76:79], v[206:209], v[172:175], v[76:79]
	global_load_lds_dwordx4 v250, s[56:57]
	v_mfma_f32_16x16x32_bf16 v[80:83], v[194:197], v[176:179], v[80:83]
	s_add_i32 m0, s35, 0x14000
	v_mfma_f32_16x16x32_bf16 v[80:83], v[198:201], v[180:183], v[80:83]
	global_load_lds_dwordx4 v251, s[58:59]
	v_mfma_f32_16x16x32_bf16 v[84:87], v[202:205], v[176:179], v[84:87]
	s_add_i32 m0, s35, 0x16000
	v_mfma_f32_16x16x32_bf16 v[84:87], v[206:209], v[180:183], v[84:87]
	global_load_lds_dwordx4 v252, s[58:59]
	v_mfma_f32_16x16x32_bf16 v[88:91], v[194:197], v[186:189], v[88:91]
	s_add_u32 s30, s30, s4
	s_addc_u32 s31, s31, s5
	v_mfma_f32_16x16x32_bf16 v[88:91], v[198:201], v[190:193], v[88:91]
	s_add_u32 s56, s56, s4
	s_addc_u32 s57, s57, s5
	v_mfma_f32_16x16x32_bf16 v[92:95], v[202:205], v[186:189], v[92:95]
	s_add_u32 s32, s32, s4
	s_addc_u32 s33, s33, s5
	v_mfma_f32_16x16x32_bf16 v[92:95], v[206:209], v[190:193], v[92:95]
	s_add_u32 s58, s58, s4
	s_addc_u32 s59, s59, s5
	s_waitcnt vmcnt(8)
	s_waitcnt lgkmcnt(0)
	s_barrier
; #define PG8_STAGE(bufoff, gbase, voff) do { _Pragma("unroll") for (int _i = 0; _i < 2; ++_i) \
;         __builtin_amdgcn_global_load_lds((const unsigned*)((const char*)(gbase) + (voff)[_i]), (PG8_LAS unsigned*)(lds + (bufoff) + ldsw + _i * 8192), 16, 0, 0); } while (0)
; #define PG8_LDA(dst, b, h) do { _Pragma("unroll") for (int m = 0; m < 4; ++m) _Pragma("unroll") for (int k = 0; k < 2; ++k) dst[m][k] = *(const PG8_LAS bf16x8*)(lds + PG8_SA(b, h) + aoff + m * 2048 + k * 1024); } while (0)
; template <class Epi, class Sched, bool ALIGN_EPI = false, bool SP2 = false>
; __device__ __forceinline__ void gemm_phase(PG8_LAS unsigned char* lds, const Gemm g, const Sched& S, const Epi& E) {
;     ...
;         const bool has_next = S.next(ui + 1, nxt);
;         const char* nA = has_next ? (const char*)g.A + (size_t)nxt.pm * tstep : cA; const char* nB = has_next ? (const char*)g.Bt + (size_t)nxt.pn * tstep : cB;
;         for (int t = 0; t < nt; t += 2) {
;             const bool last = (t == nt - 2);
;             const char* a1 = cA + (size_t)(t + 1) * kstep;
;             const char* a2 = last ? nA : cA + (size_t)(t + 2) * kstep; const char* b2 = last ? nB : cB + (size_t)(t + 2) * kstep;
;             const char* a3 = a2 + kstep; const char* b3 = b2 + kstep;
;             if (last && has_next) S.a_ready(nxt);
;             if constexpr (SP2) {
;             PG8_LDB(B0, 0, 0); PG8_LDB(B1, 0, 1); PG8_SCHED; PG8_LDA(At, 0, 0); PG8_STAGE(PG8_SA(1, 1), a1 + hstep, voffA);
;             PG8_WAIT_V(8); PG8_WAIT_L(0); PG8_BAR; PG8_MMA(0, 0, At, B0); PG8_MMA(0, 1, At, B1); PG8_BAR; PG8_SCHED;
;             PG8_LDA(At, 0, 1); PG8_STAGE(PG8_SB(0, 0), b2, voffB); PG8_STAGE(PG8_SB(0, 1), b2 + hstep, voffB); PG8_STAGE(PG8_SA(0, 0), a2, voffA);
;             PG8_WAIT_V(8); PG8_WAIT_L(0); PG8_BAR; PG8_MMA(1, 0, At, B0); PG8_MMA(1, 1, At, B1); PG8_BAR; PG8_SCHED;
;             PG8_LDB(B0, 1, 0); PG8_LDB(B1, 1, 1); PG8_SCHED; PG8_LDA(At, 1, 0); PG8_STAGE(PG8_SA(0, 1), a2 + hstep, voffA);
;             PG8_WAIT_V(8); PG8_WAIT_L(0); PG8_BAR; PG8_MMA(0, 0, At, B0); PG8_MMA(0, 1, At, B1); PG8_BAR; PG8_SCHED;
;             PG8_LDA(At, 1, 1); PG8_STAGE(PG8_SB(1, 0), b3, voffB); PG8_STAGE(PG8_SB(1, 1), b3 + hstep, voffB); PG8_STAGE(PG8_SA(1, 0), a3, voffA);
;             PG8_WAIT_V(8); PG8_WAIT_L(0); PG8_BAR; PG8_MMA(1, 0, At, B0); PG8_MMA(1, 1, At, B1); PG8_BAR; PG8_SCHED;
	v_mfma_f32_16x16x32_bf16 v[32:35], v[210:213], v[128:131], v[32:35]
	ds_read_b128 v[194:197], v247 offset:32768
	v_mfma_f32_16x16x32_bf16 v[32:35], v[214:217], v[132:135], v[32:35]
	ds_read_b128 v[198:201], v248 offset:32768
	v_mfma_f32_16x16x32_bf16 v[36:39], v[218:221], v[128:131], v[36:39]
	ds_read_b128 v[202:205], v247 offset:34816
	v_mfma_f32_16x16x32_bf16 v[36:39], v[222:225], v[132:135], v[36:39]
	ds_read_b128 v[206:209], v248 offset:34816
	v_mfma_f32_16x16x32_bf16 v[40:43], v[210:213], v[136:139], v[40:43]
	ds_read_b128 v[160:163], v245 offset:49152
	v_mfma_f32_16x16x32_bf16 v[40:43], v[214:217], v[140:143], v[40:43]
	ds_read_b128 v[164:167], v246 offset:49152
	v_mfma_f32_16x16x32_bf16 v[44:47], v[218:221], v[136:139], v[44:47]
	ds_read_b128 v[168:171], v245 offset:51200
	v_mfma_f32_16x16x32_bf16 v[44:47], v[222:225], v[140:143], v[44:47]
	ds_read_b128 v[172:175], v246 offset:51200
	v_mfma_f32_16x16x32_bf16 v[48:51], v[210:213], v[144:147], v[48:51]
	ds_read_b128 v[176:179], v245 offset:53248
	v_mfma_f32_16x16x32_bf16 v[48:51], v[214:217], v[148:151], v[48:51]
	ds_read_b128 v[180:183], v246 offset:53248
	v_mfma_f32_16x16x32_bf16 v[52:55], v[218:221], v[144:147], v[52:55]
	ds_read_b128 v[186:189], v245 offset:55296
	v_mfma_f32_16x16x32_bf16 v[52:55], v[222:225], v[148:151], v[52:55]
	ds_read_b128 v[190:193], v246 offset:55296
	v_mfma_f32_16x16x32_bf16 v[56:59], v[210:213], v[152:155], v[56:59]
	v_mfma_f32_16x16x32_bf16 v[56:59], v[214:217], v[156:159], v[56:59]
	v_mfma_f32_16x16x32_bf16 v[60:63], v[218:221], v[152:155], v[60:63]
	v_mfma_f32_16x16x32_bf16 v[60:63], v[222:225], v[156:159], v[60:63]
	s_waitcnt lgkmcnt(8)
	v_mfma_f32_16x16x32_bf16 v[0:3], v[194:197], v[128:131], v[0:3]
	v_mfma_f32_16x16x32_bf16 v[0:3], v[198:201], v[132:135], v[0:3]
	s_add_i32 m0, s35, 0x8000
	v_mfma_f32_16x16x32_bf16 v[4:7], v[202:205], v[128:131], v[4:7]
	global_load_lds_dwordx4 v249, s[30:31]
	v_mfma_f32_16x16x32_bf16 v[4:7], v[206:209], v[132:135], v[4:7]
	v_mfma_f32_16x16x32_bf16 v[8:11], v[194:197], v[136:139], v[8:11]
	s_add_i32 m0, s35, 0xa000
	v_mfma_f32_16x16x32_bf16 v[8:11], v[198:201], v[140:143], v[8:11]
	global_load_lds_dwordx4 v250, s[30:31]
	v_mfma_f32_16x16x32_bf16 v[12:15], v[202:205], v[136:139], v[12:15]
	v_mfma_f32_16x16x32_bf16 v[12:15], v[206:209], v[140:143], v[12:15]
	s_add_i32 m0, s35, 0x1c000
	v_mfma_f32_16x16x32_bf16 v[16:19], v[194:197], v[144:147], v[16:19]
	global_load_lds_dwordx4 v251, s[58:59]
	v_mfma_f32_16x16x32_bf16 v[16:19], v[198:201], v[148:151], v[16:19]
	v_mfma_f32_16x16x32_bf16 v[20:23], v[202:205], v[144:147], v[20:23]
	s_add_i32 m0, s35, 0x1e000
	v_mfma_f32_16x16x32_bf16 v[20:23], v[206:209], v[148:151], v[20:23]
	global_load_lds_dwordx4 v252, s[58:59]
	v_mfma_f32_16x16x32_bf16 v[24:27], v[194:197], v[152:155], v[24:27]
	v_mfma_f32_16x16x32_bf16 v[24:27], v[198:201], v[156:159], v[24:27]
	v_mfma_f32_16x16x32_bf16 v[28:31], v[202:205], v[152:155], v[28:31]
	v_mfma_f32_16x16x32_bf16 v[28:31], v[206:209], v[156:159], v[28:31]
	s_waitcnt vmcnt(8)
	s_waitcnt lgkmcnt(0)
	s_barrier
	v_mfma_f32_16x16x32_bf16 v[64:67], v[194:197], v[160:163], v[64:67]
	ds_read_b128 v[128:131], v245 offset:0
	v_mfma_f32_16x16x32_bf16 v[64:67], v[198:201], v[164:167], v[64:67]
	ds_read_b128 v[132:135], v246 offset:0
	v_mfma_f32_16x16x32_bf16 v[68:71], v[202:205], v[160:163], v[68:71]
	ds_read_b128 v[136:139], v245 offset:2048
	v_mfma_f32_16x16x32_bf16 v[68:71], v[206:209], v[164:167], v[68:71]
	ds_read_b128 v[140:143], v246 offset:2048
	v_mfma_f32_16x16x32_bf16 v[72:75], v[194:197], v[168:171], v[72:75]
	ds_read_b128 v[144:147], v245 offset:4096
	v_mfma_f32_16x16x32_bf16 v[72:75], v[198:201], v[172:175], v[72:75]
	ds_read_b128 v[148:151], v246 offset:4096
	v_mfma_f32_16x16x32_bf16 v[76:79], v[202:205], v[168:171], v[76:79]
	ds_read_b128 v[152:155], v245 offset:6144
	v_mfma_f32_16x16x32_bf16 v[76:79], v[206:209], v[172:175], v[76:79]
	ds_read_b128 v[156:159], v246 offset:6144
	v_mfma_f32_16x16x32_bf16 v[80:83], v[194:197], v[176:179], v[80:83]
	v_mfma_f32_16x16x32_bf16 v[80:83], v[198:201], v[180:183], v[80:83]
	v_mfma_f32_16x16x32_bf16 v[84:87], v[202:205], v[176:179], v[84:87]
	v_mfma_f32_16x16x32_bf16 v[84:87], v[206:209], v[180:183], v[84:87]
	v_mfma_f32_16x16x32_bf16 v[88:91], v[194:197], v[186:189], v[88:91]
	v_mfma_f32_16x16x32_bf16 v[88:91], v[198:201], v[190:193], v[88:91]
	v_mfma_f32_16x16x32_bf16 v[92:95], v[202:205], v[186:189], v[92:95]
	v_mfma_f32_16x16x32_bf16 v[92:95], v[206:209], v[190:193], v[92:95]
	v_mfma_f32_16x16x32_bf16 v[96:99], v[210:213], v[160:163], v[96:99]
	ds_read_b128 v[194:197], v247 offset:0
	v_mfma_f32_16x16x32_bf16 v[96:99], v[214:217], v[164:167], v[96:99]
	ds_read_b128 v[198:201], v248 offset:0
	v_mfma_f32_16x16x32_bf16 v[100:103], v[218:221], v[160:163], v[100:103]
	ds_read_b128 v[202:205], v247 offset:2048
	v_mfma_f32_16x16x32_bf16 v[100:103], v[222:225], v[164:167], v[100:103]
	ds_read_b128 v[206:209], v248 offset:2048
	v_mfma_f32_16x16x32_bf16 v[104:107], v[210:213], v[168:171], v[104:107]
	s_add_i32 m0, s35, 0xc000
	v_mfma_f32_16x16x32_bf16 v[104:107], v[214:217], v[172:175], v[104:107]
	global_load_lds_dwordx4 v249, s[56:57]
	v_mfma_f32_16x16x32_bf16 v[108:111], v[218:221], v[168:171], v[108:111]
	s_add_i32 m0, s35, 0xe000
	v_mfma_f32_16x16x32_bf16 v[108:111], v[222:225], v[172:175], v[108:111]
	global_load_lds_dwordx4 v250, s[56:57]
	v_mfma_f32_16x16x32_bf16 v[112:115], v[210:213], v[176:179], v[112:115]
	s_add_i32 m0, s35, 0x18000
	v_mfma_f32_16x16x32_bf16 v[112:115], v[214:217], v[180:183], v[112:115]
	global_load_lds_dwordx4 v251, s[32:33]
	v_mfma_f32_16x16x32_bf16 v[116:119], v[218:221], v[176:179], v[116:119]
	s_add_i32 m0, s35, 0x1a000
	v_mfma_f32_16x16x32_bf16 v[116:119], v[222:225], v[180:183], v[116:119]
	global_load_lds_dwordx4 v252, s[32:33]
	v_mfma_f32_16x16x32_bf16 v[120:123], v[210:213], v[186:189], v[120:123]
	s_add_u32 s30, s30, s4
	s_addc_u32 s31, s31, s5
	v_mfma_f32_16x16x32_bf16 v[120:123], v[214:217], v[190:193], v[120:123]
	s_add_u32 s56, s56, s4
	s_addc_u32 s57, s57, s5
	v_mfma_f32_16x16x32_bf16 v[124:127], v[218:221], v[186:189], v[124:127]
	s_add_u32 s32, s32, s4
	s_addc_u32 s33, s33, s5
	v_mfma_f32_16x16x32_bf16 v[124:127], v[222:225], v[190:193], v[124:127]
	s_add_u32 s58, s58, s4
	s_addc_u32 s59, s59, s5
	s_add_i32 s34, s34, -1
	s_cmp_lg_u32 s34, 1
	s_cbranch_scc1 .Lp5_nosw1
	s_add_u32 s45, s16, 1
	s_and_b32 s40, s45, 1
	s_lshl_b32 s4, s40, 8
	s_sub_u32 s4, 128, s4
	s_sub_u32 s5, 0, s40
	s_mul_i32 s8, s40, 3968
	s_add_u32 s30, s26, s8
	s_addc_u32 s31, s27, 0
	s_add_u32 s32, s28, s8
	s_addc_u32 s33, s29, 0
	s_add_u32 s56, s30, 0x80000
	s_addc_u32 s57, s31, 0
	s_add_u32 s58, s32, 0x80000
	s_addc_u32 s59, s33, 0

; #define PG8_STAGE(bufoff, gbase, voff) do { _Pragma("unroll") for (int _i = 0; _i < 2; ++_i) \
;         __builtin_amdgcn_global_load_lds((const unsigned*)((const char*)(gbase) + (voff)[_i]), (PG8_LAS unsigned*)(lds + (bufoff) + ldsw + _i * 8192), 16, 0, 0); } while (0)
; #define PG8_LDA(dst, b, h) do { _Pragma("unroll") for (int m = 0; m < 4; ++m) _Pragma("unroll") for (int k = 0; k < 2; ++k) dst[m][k] = *(const PG8_LAS bf16x8*)(lds + PG8_SA(b, h) + aoff + m * 2048 + k * 1024); } while (0)
; #define PG8_LDB(dst, b, h) do { _Pragma("unroll") for (int n = 0; n < 2; ++n) _Pragma("unroll") for (int k = 0; k < 2; ++k) dst[n][k] = *(const PG8_LAS bf16x8*)(lds + PG8_SB(b, h) + boff + n * 2048 + k * 1024); } while (0)
; template <class Epi, class Sched, bool ALIGN_EPI = false, bool SP2 = false>
; __device__ __forceinline__ void gemm_phase(PG8_LAS unsigned char* lds, const Gemm g, const Sched& S, const Epi& E) {
;     ...
;         for (int t = 0; t < nt; t += 2) {
;             const bool last = (t == nt - 2);
;             const char* a1 = cA + (size_t)(t + 1) * kstep;
;             const char* a2 = last ? nA : cA + (size_t)(t + 2) * kstep; const char* b2 = last ? nB : cB + (size_t)(t + 2) * kstep;
;             const char* a3 = a2 + kstep; const char* b3 = b2 + kstep;
;             if (last && has_next) S.a_ready(nxt);
;             if constexpr (SP2) {
;             PG8_LDB(B0, 0, 0); PG8_LDB(B1, 0, 1); PG8_SCHED; PG8_LDA(At, 0, 0); PG8_STAGE(PG8_SA(1, 1), a1 + hstep, voffA);
;             PG8_WAIT_V(8); PG8_WAIT_L(0); PG8_BAR; PG8_MMA(0, 0, At, B0); PG8_MMA(0, 1, At, B1); PG8_BAR; PG8_SCHED;
;             PG8_LDA(At, 0, 1); PG8_STAGE(PG8_SB(0, 0), b2, voffB); PG8_STAGE(PG8_SB(0, 1), b2 + hstep, voffB); PG8_STAGE(PG8_SA(0, 0), a2, voffA);
;             PG8_WAIT_V(8); PG8_WAIT_L(0); PG8_BAR; PG8_MMA(1, 0, At, B0); PG8_MMA(1, 1, At, B1); PG8_BAR; PG8_SCHED;
;             PG8_LDB(B0, 1, 0); PG8_LDB(B1, 1, 1); PG8_SCHED; PG8_LDA(At, 1, 0); PG8_STAGE(PG8_SA(0, 1), a2 + hstep, voffA);
;             PG8_WAIT_V(8); PG8_WAIT_L(0); PG8_BAR; PG8_MMA(0, 0, At, B0); PG8_MMA(0, 1, At, B1); PG8_BAR; PG8_SCHED;
;             PG8_LDA(At, 1, 1); PG8_STAGE(PG8_SB(1, 0), b3, voffB); PG8_STAGE(PG8_SB(1, 1), b3 + hstep, voffB); PG8_STAGE(PG8_SA(1, 0), a3, voffA);
;             PG8_WAIT_V(8); PG8_WAIT_L(0); PG8_BAR; PG8_MMA(1, 0, At, B0); PG8_MMA(1, 1, At, B1); PG8_BAR; PG8_SCHED;
.Lp6_kloop0:
	s_waitcnt vmcnt(8)
	s_waitcnt lgkmcnt(0)
	s_barrier
	v_mfma_f32_16x16x32_bf16 v[0:3], v[194:197], v[128:131], v[0:3]
	ds_read_b128 v[210:213], v247 offset:16384
	v_mfma_f32_16x16x32_bf16 v[0:3], v[198:201], v[132:135], v[0:3]
	ds_read_b128 v[214:217], v248 offset:16384
	v_mfma_f32_16x16x32_bf16 v[4:7], v[202:205], v[128:131], v[4:7]
	ds_read_b128 v[218:221], v247 offset:18432
	v_mfma_f32_16x16x32_bf16 v[4:7], v[206:209], v[132:135], v[4:7]
	ds_read_b128 v[222:225], v248 offset:18432
	v_mfma_f32_16x16x32_bf16 v[8:11], v[194:197], v[136:139], v[8:11]
	s_add_i32 m0, s35, 0x0
	v_mfma_f32_16x16x32_bf16 v[8:11], v[198:201], v[140:143], v[8:11]
	global_load_lds_dwordx4 v249, s[30:31]
	v_mfma_f32_16x16x32_bf16 v[12:15], v[202:205], v[136:139], v[12:15]
	s_add_i32 m0, s35, 0x2000
	v_mfma_f32_16x16x32_bf16 v[12:15], v[206:209], v[140:143], v[12:15]
	global_load_lds_dwordx4 v250, s[30:31]
	v_mfma_f32_16x16x32_bf16 v[16:19], v[194:197], v[144:147], v[16:19]
	s_add_i32 m0, s35, 0x10000
	v_mfma_f32_16x16x32_bf16 v[16:19], v[198:201], v[148:151], v[16:19]
	global_load_lds_dwordx4 v251, s[32:33]
	v_mfma_f32_16x16x32_bf16 v[20:23], v[202:205], v[144:147], v[20:23]
	s_add_i32 m0, s35, 0x12000
	v_mfma_f32_16x16x32_bf16 v[20:23], v[206:209], v[148:151], v[20:23]
	global_load_lds_dwordx4 v252, s[32:33]
	v_mfma_f32_16x16x32_bf16 v[24:27], v[194:197], v[152:155], v[24:27]
	ds_read_b128 v[160:163], v245 offset:16384
	v_mfma_f32_16x16x32_bf16 v[24:27], v[198:201], v[156:159], v[24:27]
	ds_read_b128 v[164:167], v246 offset:16384
	v_mfma_f32_16x16x32_bf16 v[28:31], v[202:205], v[152:155], v[28:31]
	ds_read_b128 v[168:171], v245 offset:18432
	v_mfma_f32_16x16x32_bf16 v[28:31], v[206:209], v[156:159], v[28:31]
	ds_read_b128 v[172:175], v246 offset:18432
	s_waitcnt lgkmcnt(4)
	v_mfma_f32_16x16x32_bf16 v[32:35], v[210:213], v[128:131], v[32:35]
	ds_read_b128 v[176:179], v245 offset:20480
	v_mfma_f32_16x16x32_bf16 v[32:35], v[214:217], v[132:135], v[32:35]
	ds_read_b128 v[180:183], v246 offset:20480
	v_mfma_f32_16x16x32_bf16 v[36:39], v[218:221], v[128:131], v[36:39]
	ds_read_b128 v[186:189], v245 offset:22528
	v_mfma_f32_16x16x32_bf16 v[36:39], v[222:225], v[132:135], v[36:39]
	ds_read_b128 v[190:193], v246 offset:22528
	v_mfma_f32_16x16x32_bf16 v[40:43], v[210:213], v[136:139], v[40:43]
	v_mfma_f32_16x16x32_bf16 v[40:43], v[214:217], v[140:143], v[40:43]
	v_mfma_f32_16x16x32_bf16 v[44:47], v[218:221], v[136:139], v[44:47]
	v_mfma_f32_16x16x32_bf16 v[44:47], v[222:225], v[140:143], v[44:47]
	v_mfma_f32_16x16x32_bf16 v[48:51], v[210:213], v[144:147], v[48:51]
	v_mfma_f32_16x16x32_bf16 v[48:51], v[214:217], v[148:151], v[48:51]
	v_mfma_f32_16x16x32_bf16 v[52:55], v[218:221], v[144:147], v[52:55]
	v_mfma_f32_16x16x32_bf16 v[52:55], v[222:225], v[148:151], v[52:55]
	v_mfma_f32_16x16x32_bf16 v[56:59], v[210:213], v[152:155], v[56:59]
	v_mfma_f32_16x16x32_bf16 v[56:59], v[214:217], v[156:159], v[56:59]
	v_mfma_f32_16x16x32_bf16 v[60:63], v[218:221], v[152:155], v[60:63]
	v_mfma_f32_16x16x32_bf16 v[60:63], v[222:225], v[156:159], v[60:63]
	s_waitcnt vmcnt(8)
	s_waitcnt lgkmcnt(0)
	s_barrier
	v_mfma_f32_16x16x32_bf16 v[96:99], v[210:213], v[160:163], v[96:99]
	s_add_i32 m0, s35, 0x4000
	v_mfma_f32_16x16x32_bf16 v[96:99], v[214:217], v[164:167], v[96:99]
	global_load_lds_dwordx4 v249, s[56:57]
	v_mfma_f32_16x16x32_bf16 v[100:103], v[218:221], v[160:163], v[100:103]
	s_add_i32 m0, s35, 0x6000
	v_mfma_f32_16x16x32_bf16 v[100:103], v[222:225], v[164:167], v[100:103]
	global_load_lds_dwordx4 v250, s[56:57]
	v_mfma_f32_16x16x32_bf16 v[104:107], v[210:213], v[168:171], v[104:107]
	s_add_i32 m0, s35, 0x14000
	v_mfma_f32_16x16x32_bf16 v[104:107], v[214:217], v[172:175], v[104:107]
	global_load_lds_dwordx4 v251, s[58:59]
	v_mfma_f32_16x16x32_bf16 v[108:111], v[218:221], v[168:171], v[108:111]
	s_add_i32 m0, s35, 0x16000
	v_mfma_f32_16x16x32_bf16 v[108:111], v[222:225], v[172:175], v[108:111]
	global_load_lds_dwordx4 v252, s[58:59]
	v_mfma_f32_16x16x32_bf16 v[112:115], v[210:213], v[176:179], v[112:115]
	ds_read_b128 v[128:131], v245 offset:32768
	v_mfma_f32_16x16x32_bf16 v[112:115], v[214:217], v[180:183], v[112:115]
	ds_read_b128 v[132:135], v246 offset:32768
	v_mfma_f32_16x16x32_bf16 v[116:119], v[218:221], v[176:179], v[116:119]
	ds_read_b128 v[136:139], v245 offset:34816
	v_mfma_f32_16x16x32_bf16 v[116:119], v[222:225], v[180:183], v[116:119]
	ds_read_b128 v[140:143], v246 offset:34816
	v_mfma_f32_16x16x32_bf16 v[120:123], v[210:213], v[186:189], v[120:123]
	ds_read_b128 v[144:147], v245 offset:36864
	v_mfma_f32_16x16x32_bf16 v[120:123], v[214:217], v[190:193], v[120:123]
	ds_read_b128 v[148:151], v246 offset:36864
	v_mfma_f32_16x16x32_bf16 v[124:127], v[218:221], v[186:189], v[124:127]
	ds_read_b128 v[152:155], v245 offset:38912
	v_mfma_f32_16x16x32_bf16 v[124:127], v[222:225], v[190:193], v[124:127]
	ds_read_b128 v[156:159], v246 offset:38912
	v_mfma_f32_16x16x32_bf16 v[64:67], v[194:197], v[160:163], v[64:67]
	ds_read_b128 v[210:213], v247 offset:49152
	v_mfma_f32_16x16x32_bf16 v[64:67], v[198:201], v[164:167], v[64:67]
	ds_read_b128 v[214:217], v248 offset:49152
	v_mfma_f32_16x16x32_bf16 v[68:71], v[202:205], v[160:163], v[68:71]
	ds_read_b128 v[218:221], v247 offset:51200
	v_mfma_f32_16x16x32_bf16 v[68:71], v[206:209], v[164:167], v[68:71]
	ds_read_b128 v[222:225], v248 offset:51200
	v_mfma_f32_16x16x32_bf16 v[72:75], v[194:197], v[168:171], v[72:75]
	s_add_u32 s30, s30, s4
	s_addc_u32 s31, s31, s5
	v_mfma_f32_16x16x32_bf16 v[72:75], v[198:201], v[172:175], v[72:75]
	s_add_u32 s56, s56, s4
	s_addc_u32 s57, s57, s5
	v_mfma_f32_16x16x32_bf16 v[76:79], v[202:205], v[168:171], v[76:79]
	s_add_u32 s32, s32, s4
	s_addc_u32 s33, s33, s5
	v_mfma_f32_16x16x32_bf16 v[76:79], v[206:209], v[172:175], v[76:79]
	s_add_u32 s58, s58, s4
	s_addc_u32 s59, s59, s5
	v_mfma_f32_16x16x32_bf16 v[80:83], v[194:197], v[176:179], v[80:83]
	v_mfma_f32_16x16x32_bf16 v[80:83], v[198:201], v[180:183], v[80:83]
	v_mfma_f32_16x16x32_bf16 v[84:87], v[202:205], v[176:179], v[84:87]
	v_mfma_f32_16x16x32_bf16 v[84:87], v[206:209], v[180:183], v[84:87]
	v_mfma_f32_16x16x32_bf16 v[88:91], v[194:197], v[186:189], v[88:91]
	v_mfma_f32_16x16x32_bf16 v[88:91], v[198:201], v[190:193], v[88:91]
	v_mfma_f32_16x16x32_bf16 v[92:95], v[202:205], v[186:189], v[92:95]
	v_mfma_f32_16x16x32_bf16 v[92:95], v[206:209], v[190:193], v[92:95]
	s_waitcnt vmcnt(8)
	s_waitcnt lgkmcnt(0)
	s_barrier
; #define PG8_STAGE(bufoff, gbase, voff) do { _Pragma("unroll") for (int _i = 0; _i < 2; ++_i) \
;         __builtin_amdgcn_global_load_lds((const unsigned*)((const char*)(gbase) + (voff)[_i]), (PG8_LAS unsigned*)(lds + (bufoff) + ldsw + _i * 8192), 16, 0, 0); } while (0)
; #define PG8_LDA(dst, b, h) do { _Pragma("unroll") for (int m = 0; m < 4; ++m) _Pragma("unroll") for (int k = 0; k < 2; ++k) dst[m][k] = *(const PG8_LAS bf16x8*)(lds + PG8_SA(b, h) + aoff + m * 2048 + k * 1024); } while (0)
; template <class Epi, class Sched, bool ALIGN_EPI = false, bool SP2 = false>
; __device__ __forceinline__ void gemm_phase(PG8_LAS unsigned char* lds, const Gemm g, const Sched& S, const Epi& E) {
;     ...
;         const bool has_next = S.next(ui + 1, nxt);
;         const char* nA = has_next ? (const char*)g.A + (size_t)nxt.pm * tstep : cA; const char* nB = has_next ? (const char*)g.Bt + (size_t)nxt.pn * tstep : cB;
;         for (int t = 0; t < nt; t += 2) {
;             const bool last = (t == nt - 2);
;             const char* a1 = cA + (size_t)(t + 1) * kstep;
;             const char* a2 = last ? nA : cA + (size_t)(t + 2) * kstep; const char* b2 = last ? nB : cB + (size_t)(t + 2) * kstep;
;             const char* a3 = a2 + kstep; const char* b3 = b2 + kstep;
;             if (last && has_next) S.a_ready(nxt);
;             if constexpr (SP2) {
;             PG8_LDB(B0, 0, 0); PG8_LDB(B1, 0, 1); PG8_SCHED; PG8_LDA(At, 0, 0); PG8_STAGE(PG8_SA(1, 1), a1 + hstep, voffA);
;             PG8_WAIT_V(8); PG8_WAIT_L(0); PG8_BAR; PG8_MMA(0, 0, At, B0); PG8_MMA(0, 1, At, B1); PG8_BAR; PG8_SCHED;
;             PG8_LDA(At, 0, 1); PG8_STAGE(PG8_SB(0, 0), b2, voffB); PG8_STAGE(PG8_SB(0, 1), b2 + hstep, voffB); PG8_STAGE(PG8_SA(0, 0), a2, voffA);
;             PG8_WAIT_V(8); PG8_WAIT_L(0); PG8_BAR; PG8_MMA(1, 0, At, B0); PG8_MMA(1, 1, At, B1); PG8_BAR; PG8_SCHED;
;             PG8_LDB(B0, 1, 0); PG8_LDB(B1, 1, 1); PG8_SCHED; PG8_LDA(At, 1, 0); PG8_STAGE(PG8_SA(0, 1), a2 + hstep, voffA);
;             PG8_WAIT_V(8); PG8_WAIT_L(0); PG8_BAR; PG8_MMA(0, 0, At, B0); PG8_MMA(0, 1, At, B1); PG8_BAR; PG8_SCHED;
;             PG8_LDA(At, 1, 1); PG8_STAGE(PG8_SB(1, 0), b3, voffB); PG8_STAGE(PG8_SB(1, 1), b3 + hstep, voffB); PG8_STAGE(PG8_SA(1, 0), a3, voffA);
;             PG8_WAIT_V(8); PG8_WAIT_L(0); PG8_BAR; PG8_MMA(1, 0, At, B0); PG8_MMA(1, 1, At, B1); PG8_BAR; PG8_SCHED;
	v_mfma_f32_16x16x32_bf16 v[32:35], v[210:213], v[128:131], v[32:35]
	ds_read_b128 v[194:197], v247 offset:32768
	v_mfma_f32_16x16x32_bf16 v[32:35], v[214:217], v[132:135], v[32:35]
	ds_read_b128 v[198:201], v248 offset:32768
	v_mfma_f32_16x16x32_bf16 v[36:39], v[218:221], v[128:131], v[36:39]
	ds_read_b128 v[202:205], v247 offset:34816
	v_mfma_f32_16x16x32_bf16 v[36:39], v[222:225], v[132:135], v[36:39]
	ds_read_b128 v[206:209], v248 offset:34816
	v_mfma_f32_16x16x32_bf16 v[40:43], v[210:213], v[136:139], v[40:43]
	s_add_i32 m0, s35, 0x8000
	v_mfma_f32_16x16x32_bf16 v[40:43], v[214:217], v[140:143], v[40:43]
	global_load_lds_dwordx4 v249, s[30:31]
	v_mfma_f32_16x16x32_bf16 v[44:47], v[218:221], v[136:139], v[44:47]
	s_add_i32 m0, s35, 0xa000
	v_mfma_f32_16x16x32_bf16 v[44:47], v[222:225], v[140:143], v[44:47]
	global_load_lds_dwordx4 v250, s[30:31]
	v_mfma_f32_16x16x32_bf16 v[48:51], v[210:213], v[144:147], v[48:51]
	s_add_i32 m0, s35, 0x1c000
	v_mfma_f32_16x16x32_bf16 v[48:51], v[214:217], v[148:151], v[48:51]
	global_load_lds_dwordx4 v251, s[58:59]
	v_mfma_f32_16x16x32_bf16 v[52:55], v[218:221], v[144:147], v[52:55]
	s_add_i32 m0, s35, 0x1e000
	v_mfma_f32_16x16x32_bf16 v[52:55], v[222:225], v[148:151], v[52:55]
	global_load_lds_dwordx4 v252, s[58:59]
	v_mfma_f32_16x16x32_bf16 v[56:59], v[210:213], v[152:155], v[56:59]
	ds_read_b128 v[160:163], v245 offset:49152
	v_mfma_f32_16x16x32_bf16 v[56:59], v[214:217], v[156:159], v[56:59]
	ds_read_b128 v[164:167], v246 offset:49152
	v_mfma_f32_16x16x32_bf16 v[60:63], v[218:221], v[152:155], v[60:63]
	ds_read_b128 v[168:171], v245 offset:51200
	v_mfma_f32_16x16x32_bf16 v[60:63], v[222:225], v[156:159], v[60:63]
	ds_read_b128 v[172:175], v246 offset:51200
	s_waitcnt lgkmcnt(4)
	v_mfma_f32_16x16x32_bf16 v[0:3], v[194:197], v[128:131], v[0:3]
	ds_read_b128 v[176:179], v245 offset:53248
	v_mfma_f32_16x16x32_bf16 v[0:3], v[198:201], v[132:135], v[0:3]
	ds_read_b128 v[180:183], v246 offset:53248
	v_mfma_f32_16x16x32_bf16 v[4:7], v[202:205], v[128:131], v[4:7]
	ds_read_b128 v[186:189], v245 offset:55296
	v_mfma_f32_16x16x32_bf16 v[4:7], v[206:209], v[132:135], v[4:7]
	ds_read_b128 v[190:193], v246 offset:55296
	v_mfma_f32_16x16x32_bf16 v[8:11], v[194:197], v[136:139], v[8:11]
	v_mfma_f32_16x16x32_bf16 v[8:11], v[198:201], v[140:143], v[8:11]
	v_mfma_f32_16x16x32_bf16 v[12:15], v[202:205], v[136:139], v[12:15]
	v_mfma_f32_16x16x32_bf16 v[12:15], v[206:209], v[140:143], v[12:15]
	v_mfma_f32_16x16x32_bf16 v[16:19], v[194:197], v[144:147], v[16:19]
	v_mfma_f32_16x16x32_bf16 v[16:19], v[198:201], v[148:151], v[16:19]
	v_mfma_f32_16x16x32_bf16 v[20:23], v[202:205], v[144:147], v[20:23]
	v_mfma_f32_16x16x32_bf16 v[20:23], v[206:209], v[148:151], v[20:23]
	v_mfma_f32_16x16x32_bf16 v[24:27], v[194:197], v[152:155], v[24:27]
	v_mfma_f32_16x16x32_bf16 v[24:27], v[198:201], v[156:159], v[24:27]
	v_mfma_f32_16x16x32_bf16 v[28:31], v[202:205], v[152:155], v[28:31]
	v_mfma_f32_16x16x32_bf16 v[28:31], v[206:209], v[156:159], v[28:31]
	s_waitcnt vmcnt(8)
	s_waitcnt lgkmcnt(0)
	s_barrier
	v_mfma_f32_16x16x32_bf16 v[64:67], v[194:197], v[160:163], v[64:67]
	s_add_i32 m0, s35, 0xc000
	v_mfma_f32_16x16x32_bf16 v[64:67], v[198:201], v[164:167], v[64:67]
	global_load_lds_dwordx4 v249, s[56:57]
	v_mfma_f32_16x16x32_bf16 v[68:71], v[202:205], v[160:163], v[68:71]
	s_add_i32 m0, s35, 0xe000
	v_mfma_f32_16x16x32_bf16 v[68:71], v[206:209], v[164:167], v[68:71]
	global_load_lds_dwordx4 v250, s[56:57]
	v_mfma_f32_16x16x32_bf16 v[72:75], v[194:197], v[168:171], v[72:75]
	s_add_i32 m0, s35, 0x18000
	v_mfma_f32_16x16x32_bf16 v[72:75], v[198:201], v[172:175], v[72:75]
	global_load_lds_dwordx4 v251, s[32:33]
	v_mfma_f32_16x16x32_bf16 v[76:79], v[202:205], v[168:171], v[76:79]
	s_add_i32 m0, s35, 0x1a000
	v_mfma_f32_16x16x32_bf16 v[76:79], v[206:209], v[172:175], v[76:79]
	global_load_lds_dwordx4 v252, s[32:33]
	v_mfma_f32_16x16x32_bf16 v[80:83], v[194:197], v[176:179], v[80:83]
	ds_read_b128 v[128:131], v245 offset:0
	v_mfma_f32_16x16x32_bf16 v[80:83], v[198:201], v[180:183], v[80:83]
	ds_read_b128 v[132:135], v246 offset:0
	v_mfma_f32_16x16x32_bf16 v[84:87], v[202:205], v[176:179], v[84:87]
	ds_read_b128 v[136:139], v245 offset:2048
	v_mfma_f32_16x16x32_bf16 v[84:87], v[206:209], v[180:183], v[84:87]
	ds_read_b128 v[140:143], v246 offset:2048
	v_mfma_f32_16x16x32_bf16 v[88:91], v[194:197], v[186:189], v[88:91]
	ds_read_b128 v[144:147], v245 offset:4096
	v_mfma_f32_16x16x32_bf16 v[88:91], v[198:201], v[190:193], v[88:91]
	ds_read_b128 v[148:151], v246 offset:4096
	v_mfma_f32_16x16x32_bf16 v[92:95], v[202:205], v[186:189], v[92:95]
	ds_read_b128 v[152:155], v245 offset:6144
	v_mfma_f32_16x16x32_bf16 v[92:95], v[206:209], v[190:193], v[92:95]
	ds_read_b128 v[156:159], v246 offset:6144
	v_mfma_f32_16x16x32_bf16 v[96:99], v[210:213], v[160:163], v[96:99]
	ds_read_b128 v[194:197], v247 offset:0
	v_mfma_f32_16x16x32_bf16 v[96:99], v[214:217], v[164:167], v[96:99]
	ds_read_b128 v[198:201], v248 offset:0
	v_mfma_f32_16x16x32_bf16 v[100:103], v[218:221], v[160:163], v[100:103]
	ds_read_b128 v[202:205], v247 offset:2048
	v_mfma_f32_16x16x32_bf16 v[100:103], v[222:225], v[164:167], v[100:103]
	ds_read_b128 v[206:209], v248 offset:2048
	v_mfma_f32_16x16x32_bf16 v[104:107], v[210:213], v[168:171], v[104:107]
	s_add_u32 s30, s30, s4
	s_addc_u32 s31, s31, s5
	v_mfma_f32_16x16x32_bf16 v[104:107], v[214:217], v[172:175], v[104:107]
	s_add_u32 s56, s56, s4
	s_addc_u32 s57, s57, s5
	v_mfma_f32_16x16x32_bf16 v[108:111], v[218:221], v[168:171], v[108:111]
	s_add_u32 s32, s32, s4
	s_addc_u32 s33, s33, s5
	v_mfma_f32_16x16x32_bf16 v[108:111], v[222:225], v[172:175], v[108:111]
	s_add_u32 s58, s58, s4
	s_addc_u32 s59, s59, s5
	v_mfma_f32_16x16x32_bf16 v[112:115], v[210:213], v[176:179], v[112:115]
	v_mfma_f32_16x16x32_bf16 v[112:115], v[214:217], v[180:183], v[112:115]
	v_mfma_f32_16x16x32_bf16 v[116:119], v[218:221], v[176:179], v[116:119]
	v_mfma_f32_16x16x32_bf16 v[116:119], v[222:225], v[180:183], v[116:119]
	v_mfma_f32_16x16x32_bf16 v[120:123], v[210:213], v[186:189], v[120:123]
	v_mfma_f32_16x16x32_bf16 v[120:123], v[214:217], v[190:193], v[120:123]
	v_mfma_f32_16x16x32_bf16 v[124:127], v[218:221], v[186:189], v[124:127]
	v_mfma_f32_16x16x32_bf16 v[124:127], v[222:225], v[190:193], v[124:127]
	s_add_i32 s34, s34, -1
	s_cmp_lg_u32 s34, 1
	s_cbranch_scc1 .Lp6_nosw0
	s_add_u32 s45, s16, 1
	s_and_b32 s40, s45, 1
	s_lshl_b32 s4, s40, 8
	s_sub_u32 s4, 128, s4
	s_sub_u32 s5, 0, s40
	s_mul_i32 s8, s40, 11136
	s_add_u32 s30, s26, s8
	s_addc_u32 s31, s27, 0
	s_add_u32 s32, s28, s8
	s_addc_u32 s33, s29, 0
	s_add_u32 s56, s30, 0x160000
	s_addc_u32 s57, s31, 0
	s_add_u32 s58, s32, 0x160000
	s_addc_u32 s59, s33, 0

; #define PG8_STAGE(bufoff, gbase, voff) do { _Pragma("unroll") for (int _i = 0; _i < 2; ++_i) \
;         __builtin_amdgcn_global_load_lds((const unsigned*)((const char*)(gbase) + (voff)[_i]), (PG8_LAS unsigned*)(lds + (bufoff) + ldsw + _i * 8192), 16, 0, 0); } while (0)
; #define PG8_LDA(dst, b, h) do { _Pragma("unroll") for (int m = 0; m < 4; ++m) _Pragma("unroll") for (int k = 0; k < 2; ++k) dst[m][k] = *(const PG8_LAS bf16x8*)(lds + PG8_SA(b, h) + aoff + m * 2048 + k * 1024); } while (0)
; #define PG8_LDB(dst, b, h) do { _Pragma("unroll") for (int n = 0; n < 2; ++n) _Pragma("unroll") for (int k = 0; k < 2; ++k) dst[n][k] = *(const PG8_LAS bf16x8*)(lds + PG8_SB(b, h) + boff + n * 2048 + k * 1024); } while (0)
; #define PG8_MMA(ai, bj, At, Bt) do { __builtin_amdgcn_s_setprio(1); _Pragma("unroll") for (int m = 0; m < 4; ++m) _Pragma("unroll") for (int n = 0; n < 2; ++n) _Pragma("unroll") for (int k = 0; k < 2; ++k) \
;         acc[ai][bj][m][n] = __builtin_amdgcn_mfma_f32_16x16x32_bf16(Bt[n][k], At[m][k], acc[ai][bj][m][n], 0, 0, 0); __builtin_amdgcn_s_setprio(0); } while (0)
; #define PG8_WAIT_V(n) asm volatile("s_waitcnt vmcnt(" #n ")" ::: "memory")
; template <class Epi, class Sched, bool ALIGN_EPI = false, bool SP2 = false>
; __device__ __forceinline__ void gemm_phase(PG8_LAS unsigned char* lds, const Gemm g, const Sched& S, const Epi& E) {
;     ...
;             PG8_LDB(B0, 0, 0); PG8_LDB(B1, 0, 1); PG8_SCHED; PG8_LDA(At, 0, 0); PG8_STAGE(PG8_SA(1, 1), a1 + hstep, voffA);
;             PG8_WAIT_V(8); PG8_WAIT_L(0); PG8_BAR; PG8_MMA(0, 0, At, B0); PG8_MMA(0, 1, At, B1); PG8_BAR; PG8_SCHED;
;             PG8_LDA(At, 0, 1); PG8_STAGE(PG8_SB(0, 0), b2, voffB); PG8_STAGE(PG8_SB(0, 1), b2 + hstep, voffB); PG8_STAGE(PG8_SA(0, 0), a2, voffA);
;             PG8_WAIT_V(8); PG8_WAIT_L(0); PG8_BAR; PG8_MMA(1, 0, At, B0); PG8_MMA(1, 1, At, B1); PG8_BAR; PG8_SCHED;
;             PG8_LDB(B0, 1, 0); PG8_LDB(B1, 1, 1); PG8_SCHED; PG8_LDA(At, 1, 0); PG8_STAGE(PG8_SA(0, 1), a2 + hstep, voffA);
;             PG8_WAIT_V(8); PG8_WAIT_L(0); PG8_BAR; PG8_MMA(0, 0, At, B0); PG8_MMA(0, 1, At, B1); PG8_BAR; PG8_SCHED;
;             PG8_LDA(At, 1, 1); PG8_STAGE(PG8_SB(1, 0), b3, voffB); PG8_STAGE(PG8_SB(1, 1), b3 + hstep, voffB); PG8_STAGE(PG8_SA(1, 0), a3, voffA);
;             PG8_WAIT_V(8); PG8_WAIT_L(0); PG8_BAR; PG8_MMA(1, 0, At, B0); PG8_MMA(1, 1, At, B1); PG8_BAR; PG8_SCHED;
.Lp6_kloop1:
	s_waitcnt vmcnt(8)
	s_waitcnt lgkmcnt(0)
	s_barrier
	v_mfma_f32_16x16x32_bf16 v[0:3], v[194:197], v[128:131], v[0:3]
	ds_read_b128 v[210:213], v247 offset:16384
	v_mfma_f32_16x16x32_bf16 v[0:3], v[198:201], v[132:135], v[0:3]
	ds_read_b128 v[214:217], v248 offset:16384
	v_mfma_f32_16x16x32_bf16 v[4:7], v[202:205], v[128:131], v[4:7]
	ds_read_b128 v[218:221], v247 offset:18432
	v_mfma_f32_16x16x32_bf16 v[4:7], v[206:209], v[132:135], v[4:7]
	ds_read_b128 v[222:225], v248 offset:18432
	v_mfma_f32_16x16x32_bf16 v[8:11], v[194:197], v[136:139], v[8:11]
	ds_read_b128 v[160:163], v245 offset:16384
	v_mfma_f32_16x16x32_bf16 v[8:11], v[198:201], v[140:143], v[8:11]
	ds_read_b128 v[164:167], v246 offset:16384
	v_mfma_f32_16x16x32_bf16 v[12:15], v[202:205], v[136:139], v[12:15]
	ds_read_b128 v[168:171], v245 offset:18432
	v_mfma_f32_16x16x32_bf16 v[12:15], v[206:209], v[140:143], v[12:15]
	ds_read_b128 v[172:175], v246 offset:18432
	v_mfma_f32_16x16x32_bf16 v[16:19], v[194:197], v[144:147], v[16:19]
	ds_read_b128 v[176:179], v245 offset:20480
	v_mfma_f32_16x16x32_bf16 v[16:19], v[198:201], v[148:151], v[16:19]
	ds_read_b128 v[180:183], v246 offset:20480
	v_mfma_f32_16x16x32_bf16 v[20:23], v[202:205], v[144:147], v[20:23]
	ds_read_b128 v[186:189], v245 offset:22528
	v_mfma_f32_16x16x32_bf16 v[20:23], v[206:209], v[148:151], v[20:23]
	ds_read_b128 v[190:193], v246 offset:22528
	v_mfma_f32_16x16x32_bf16 v[24:27], v[194:197], v[152:155], v[24:27]
	v_mfma_f32_16x16x32_bf16 v[24:27], v[198:201], v[156:159], v[24:27]
	v_mfma_f32_16x16x32_bf16 v[28:31], v[202:205], v[152:155], v[28:31]
	v_mfma_f32_16x16x32_bf16 v[28:31], v[206:209], v[156:159], v[28:31]
	s_waitcnt lgkmcnt(8)
	v_mfma_f32_16x16x32_bf16 v[32:35], v[210:213], v[128:131], v[32:35]
	v_mfma_f32_16x16x32_bf16 v[32:35], v[214:217], v[132:135], v[32:35]
	s_add_i32 m0, s35, 0x0
	v_mfma_f32_16x16x32_bf16 v[36:39], v[218:221], v[128:131], v[36:39]
	global_load_lds_dwordx4 v249, s[30:31]
	v_mfma_f32_16x16x32_bf16 v[36:39], v[222:225], v[132:135], v[36:39]
	v_mfma_f32_16x16x32_bf16 v[40:43], v[210:213], v[136:139], v[40:43]
	s_add_i32 m0, s35, 0x2000
	v_mfma_f32_16x16x32_bf16 v[40:43], v[214:217], v[140:143], v[40:43]
	global_load_lds_dwordx4 v250, s[30:31]
	v_mfma_f32_16x16x32_bf16 v[44:47], v[218:221], v[136:139], v[44:47]
	v_mfma_f32_16x16x32_bf16 v[44:47], v[222:225], v[140:143], v[44:47]
	s_add_i32 m0, s35, 0x10000
	v_mfma_f32_16x16x32_bf16 v[48:51], v[210:213], v[144:147], v[48:51]
	global_load_lds_dwordx4 v251, s[32:33]
	v_mfma_f32_16x16x32_bf16 v[48:51], v[214:217], v[148:151], v[48:51]
	v_mfma_f32_16x16x32_bf16 v[52:55], v[218:221], v[144:147], v[52:55]
	s_add_i32 m0, s35, 0x12000
	v_mfma_f32_16x16x32_bf16 v[52:55], v[222:225], v[148:151], v[52:55]
	global_load_lds_dwordx4 v252, s[32:33]
	v_mfma_f32_16x16x32_bf16 v[56:59], v[210:213], v[152:155], v[56:59]
	v_mfma_f32_16x16x32_bf16 v[56:59], v[214:217], v[156:159], v[56:59]
	v_mfma_f32_16x16x32_bf16 v[60:63], v[218:221], v[152:155], v[60:63]
	v_mfma_f32_16x16x32_bf16 v[60:63], v[222:225], v[156:159], v[60:63]
	s_waitcnt vmcnt(8)
	s_waitcnt lgkmcnt(0)
	s_barrier
	v_mfma_f32_16x16x32_bf16 v[96:99], v[210:213], v[160:163], v[96:99]
	ds_read_b128 v[128:131], v245 offset:32768
	v_mfma_f32_16x16x32_bf16 v[96:99], v[214:217], v[164:167], v[96:99]
	ds_read_b128 v[132:135], v246 offset:32768
	v_mfma_f32_16x16x32_bf16 v[100:103], v[218:221], v[160:163], v[100:103]
	ds_read_b128 v[136:139], v245 offset:34816
	v_mfma_f32_16x16x32_bf16 v[100:103], v[222:225], v[164:167], v[100:103]
	ds_read_b128 v[140:143], v246 offset:34816
	v_mfma_f32_16x16x32_bf16 v[104:107], v[210:213], v[168:171], v[104:107]
	ds_read_b128 v[144:147], v245 offset:36864
	v_mfma_f32_16x16x32_bf16 v[104:107], v[214:217], v[172:175], v[104:107]
	ds_read_b128 v[148:151], v246 offset:36864
	v_mfma_f32_16x16x32_bf16 v[108:111], v[218:221], v[168:171], v[108:111]
	ds_read_b128 v[152:155], v245 offset:38912
	v_mfma_f32_16x16x32_bf16 v[108:111], v[222:225], v[172:175], v[108:111]
	ds_read_b128 v[156:159], v246 offset:38912
	v_mfma_f32_16x16x32_bf16 v[112:115], v[210:213], v[176:179], v[112:115]
	v_mfma_f32_16x16x32_bf16 v[112:115], v[214:217], v[180:183], v[112:115]
	v_mfma_f32_16x16x32_bf16 v[116:119], v[218:221], v[176:179], v[116:119]
	v_mfma_f32_16x16x32_bf16 v[116:119], v[222:225], v[180:183], v[116:119]
	v_mfma_f32_16x16x32_bf16 v[120:123], v[210:213], v[186:189], v[120:123]
	v_mfma_f32_16x16x32_bf16 v[120:123], v[214:217], v[190:193], v[120:123]
	v_mfma_f32_16x16x32_bf16 v[124:127], v[218:221], v[186:189], v[124:127]
	v_mfma_f32_16x16x32_bf16 v[124:127], v[222:225], v[190:193], v[124:127]
	v_mfma_f32_16x16x32_bf16 v[64:67], v[194:197], v[160:163], v[64:67]
	ds_read_b128 v[210:213], v247 offset:49152
	v_mfma_f32_16x16x32_bf16 v[64:67], v[198:201], v[164:167], v[64:67]
	ds_read_b128 v[214:217], v248 offset:49152
	v_mfma_f32_16x16x32_bf16 v[68:71], v[202:205], v[160:163], v[68:71]
	ds_read_b128 v[218:221], v247 offset:51200
	v_mfma_f32_16x16x32_bf16 v[68:71], v[206:209], v[164:167], v[68:71]
	ds_read_b128 v[222:225], v248 offset:51200
	v_mfma_f32_16x16x32_bf16 v[72:75], v[194:197], v[168:171], v[72:75]
	s_add_i32 m0, s35, 0x4000
	v_mfma_f32_16x16x32_bf16 v[72:75], v[198:201], v[172:175], v[72:75]
	global_load_lds_dwordx4 v249, s[56:57]
	v_mfma_f32_16x16x32_bf16 v[76:79], v[202:205], v[168:171], v[76:79]
	s_add_i32 m0, s35, 0x6000
	v_mfma_f32_16x16x32_bf16 v[76:79], v[206:209], v[172:175], v[76:79]
	global_load_lds_dwordx4 v250, s[56:57]
	v_mfma_f32_16x16x32_bf16 v[80:83], v[194:197], v[176:179], v[80:83]
	s_add_i32 m0, s35, 0x14000
	v_mfma_f32_16x16x32_bf16 v[80:83], v[198:201], v[180:183], v[80:83]
	global_load_lds_dwordx4 v251, s[58:59]
	v_mfma_f32_16x16x32_bf16 v[84:87], v[202:205], v[176:179], v[84:87]
	s_add_i32 m0, s35, 0x16000
	v_mfma_f32_16x16x32_bf16 v[84:87], v[206:209], v[180:183], v[84:87]
	global_load_lds_dwordx4 v252, s[58:59]
	v_mfma_f32_16x16x32_bf16 v[88:91], v[194:197], v[186:189], v[88:91]
	s_add_u32 s30, s30, s4
	s_addc_u32 s31, s31, s5
	v_mfma_f32_16x16x32_bf16 v[88:91], v[198:201], v[190:193], v[88:91]
	s_add_u32 s56, s56, s4
	s_addc_u32 s57, s57, s5
	v_mfma_f32_16x16x32_bf16 v[92:95], v[202:205], v[186:189], v[92:95]
	s_add_u32 s32, s32, s4
	s_addc_u32 s33, s33, s5
	v_mfma_f32_16x16x32_bf16 v[92:95], v[206:209], v[190:193], v[92:95]
	s_add_u32 s58, s58, s4
	s_addc_u32 s59, s59, s5
	s_waitcnt vmcnt(8)
	s_waitcnt lgkmcnt(0)
	s_barrier
; #define PG8_STAGE(bufoff, gbase, voff) do { _Pragma("unroll") for (int _i = 0; _i < 2; ++_i) \
;         __builtin_amdgcn_global_load_lds((const unsigned*)((const char*)(gbase) + (voff)[_i]), (PG8_LAS unsigned*)(lds + (bufoff) + ldsw + _i * 8192), 16, 0, 0); } while (0)
; #define PG8_LDA(dst, b, h) do { _Pragma("unroll") for (int m = 0; m < 4; ++m) _Pragma("unroll") for (int k = 0; k < 2; ++k) dst[m][k] = *(const PG8_LAS bf16x8*)(lds + PG8_SA(b, h) + aoff + m * 2048 + k * 1024); } while (0)
; #define PG8_WAIT_V(n) asm volatile("s_waitcnt vmcnt(" #n ")" ::: "memory")
; template <class Epi, class Sched, bool ALIGN_EPI = false, bool SP2 = false>
; __device__ __forceinline__ void gemm_phase(PG8_LAS unsigned char* lds, const Gemm g, const Sched& S, const Epi& E) {
;     ...
;         const bool has_next = S.next(ui + 1, nxt);
;         const char* nA = has_next ? (const char*)g.A + (size_t)nxt.pm * tstep : cA; const char* nB = has_next ? (const char*)g.Bt + (size_t)nxt.pn * tstep : cB;
;         for (int t = 0; t < nt; t += 2) {
;             const bool last = (t == nt - 2);
;             const char* a1 = cA + (size_t)(t + 1) * kstep;
;             const char* a2 = last ? nA : cA + (size_t)(t + 2) * kstep; const char* b2 = last ? nB : cB + (size_t)(t + 2) * kstep;
;             const char* a3 = a2 + kstep; const char* b3 = b2 + kstep;
;     ...
;             PG8_LDB(B0, 0, 0); PG8_LDB(B1, 0, 1); PG8_SCHED; PG8_LDA(At, 0, 0); PG8_STAGE(PG8_SA(1, 1), a1 + hstep, voffA);
;             PG8_WAIT_V(8); PG8_WAIT_L(0); PG8_BAR; PG8_MMA(0, 0, At, B0); PG8_MMA(0, 1, At, B1); PG8_BAR; PG8_SCHED;
;             PG8_LDA(At, 0, 1); PG8_STAGE(PG8_SB(0, 0), b2, voffB); PG8_STAGE(PG8_SB(0, 1), b2 + hstep, voffB); PG8_STAGE(PG8_SA(0, 0), a2, voffA);
;             PG8_WAIT_V(8); PG8_WAIT_L(0); PG8_BAR; PG8_MMA(1, 0, At, B0); PG8_MMA(1, 1, At, B1); PG8_BAR; PG8_SCHED;
;             PG8_LDB(B0, 1, 0); PG8_LDB(B1, 1, 1); PG8_SCHED; PG8_LDA(At, 1, 0); PG8_STAGE(PG8_SA(0, 1), a2 + hstep, voffA);
;             PG8_WAIT_V(8); PG8_WAIT_L(0); PG8_BAR; PG8_MMA(0, 0, At, B0); PG8_MMA(0, 1, At, B1); PG8_BAR; PG8_SCHED;
;             PG8_LDA(At, 1, 1); PG8_STAGE(PG8_SB(1, 0), b3, voffB); PG8_STAGE(PG8_SB(1, 1), b3 + hstep, voffB); PG8_STAGE(PG8_SA(1, 0), a3, voffA);
;             PG8_WAIT_V(8); PG8_WAIT_L(0); PG8_BAR; PG8_MMA(1, 0, At, B0); PG8_MMA(1, 1, At, B1); PG8_BAR; PG8_SCHED;
	v_mfma_f32_16x16x32_bf16 v[32:35], v[210:213], v[128:131], v[32:35]
	ds_read_b128 v[194:197], v247 offset:32768
	v_mfma_f32_16x16x32_bf16 v[32:35], v[214:217], v[132:135], v[32:35]
	ds_read_b128 v[198:201], v248 offset:32768
	v_mfma_f32_16x16x32_bf16 v[36:39], v[218:221], v[128:131], v[36:39]
	ds_read_b128 v[202:205], v247 offset:34816
	v_mfma_f32_16x16x32_bf16 v[36:39], v[222:225], v[132:135], v[36:39]
	ds_read_b128 v[206:209], v248 offset:34816
	v_mfma_f32_16x16x32_bf16 v[40:43], v[210:213], v[136:139], v[40:43]
	ds_read_b128 v[160:163], v245 offset:49152
	v_mfma_f32_16x16x32_bf16 v[40:43], v[214:217], v[140:143], v[40:43]
	ds_read_b128 v[164:167], v246 offset:49152
	v_mfma_f32_16x16x32_bf16 v[44:47], v[218:221], v[136:139], v[44:47]
	ds_read_b128 v[168:171], v245 offset:51200
	v_mfma_f32_16x16x32_bf16 v[44:47], v[222:225], v[140:143], v[44:47]
	ds_read_b128 v[172:175], v246 offset:51200
	v_mfma_f32_16x16x32_bf16 v[48:51], v[210:213], v[144:147], v[48:51]
	ds_read_b128 v[176:179], v245 offset:53248
	v_mfma_f32_16x16x32_bf16 v[48:51], v[214:217], v[148:151], v[48:51]
	ds_read_b128 v[180:183], v246 offset:53248
	v_mfma_f32_16x16x32_bf16 v[52:55], v[218:221], v[144:147], v[52:55]
	ds_read_b128 v[186:189], v245 offset:55296
	v_mfma_f32_16x16x32_bf16 v[52:55], v[222:225], v[148:151], v[52:55]
	ds_read_b128 v[190:193], v246 offset:55296
	v_mfma_f32_16x16x32_bf16 v[56:59], v[210:213], v[152:155], v[56:59]
	v_mfma_f32_16x16x32_bf16 v[56:59], v[214:217], v[156:159], v[56:59]
	v_mfma_f32_16x16x32_bf16 v[60:63], v[218:221], v[152:155], v[60:63]
	v_mfma_f32_16x16x32_bf16 v[60:63], v[222:225], v[156:159], v[60:63]
	s_waitcnt lgkmcnt(8)
	v_mfma_f32_16x16x32_bf16 v[0:3], v[194:197], v[128:131], v[0:3]
	v_mfma_f32_16x16x32_bf16 v[0:3], v[198:201], v[132:135], v[0:3]
	s_add_i32 m0, s35, 0x8000
	v_mfma_f32_16x16x32_bf16 v[4:7], v[202:205], v[128:131], v[4:7]
	global_load_lds_dwordx4 v249, s[30:31]
	v_mfma_f32_16x16x32_bf16 v[4:7], v[206:209], v[132:135], v[4:7]
	v_mfma_f32_16x16x32_bf16 v[8:11], v[194:197], v[136:139], v[8:11]
	s_add_i32 m0, s35, 0xa000
	v_mfma_f32_16x16x32_bf16 v[8:11], v[198:201], v[140:143], v[8:11]
	global_load_lds_dwordx4 v250, s[30:31]
	v_mfma_f32_16x16x32_bf16 v[12:15], v[202:205], v[136:139], v[12:15]
	v_mfma_f32_16x16x32_bf16 v[12:15], v[206:209], v[140:143], v[12:15]
	s_add_i32 m0, s35, 0x1c000
	v_mfma_f32_16x16x32_bf16 v[16:19], v[194:197], v[144:147], v[16:19]
	global_load_lds_dwordx4 v251, s[58:59]
	v_mfma_f32_16x16x32_bf16 v[16:19], v[198:201], v[148:151], v[16:19]
	v_mfma_f32_16x16x32_bf16 v[20:23], v[202:205], v[144:147], v[20:23]
	s_add_i32 m0, s35, 0x1e000
	v_mfma_f32_16x16x32_bf16 v[20:23], v[206:209], v[148:151], v[20:23]
	global_load_lds_dwordx4 v252, s[58:59]
	v_mfma_f32_16x16x32_bf16 v[24:27], v[194:197], v[152:155], v[24:27]
	v_mfma_f32_16x16x32_bf16 v[24:27], v[198:201], v[156:159], v[24:27]
	v_mfma_f32_16x16x32_bf16 v[28:31], v[202:205], v[152:155], v[28:31]
	v_mfma_f32_16x16x32_bf16 v[28:31], v[206:209], v[156:159], v[28:31]
	s_waitcnt vmcnt(8)
	s_waitcnt lgkmcnt(0)
	s_barrier
	v_mfma_f32_16x16x32_bf16 v[64:67], v[194:197], v[160:163], v[64:67]
	ds_read_b128 v[128:131], v245 offset:0
	v_mfma_f32_16x16x32_bf16 v[64:67], v[198:201], v[164:167], v[64:67]
	ds_read_b128 v[132:135], v246 offset:0
	v_mfma_f32_16x16x32_bf16 v[68:71], v[202:205], v[160:163], v[68:71]
	ds_read_b128 v[136:139], v245 offset:2048
	v_mfma_f32_16x16x32_bf16 v[68:71], v[206:209], v[164:167], v[68:71]
	ds_read_b128 v[140:143], v246 offset:2048
	v_mfma_f32_16x16x32_bf16 v[72:75], v[194:197], v[168:171], v[72:75]
	ds_read_b128 v[144:147], v245 offset:4096
	v_mfma_f32_16x16x32_bf16 v[72:75], v[198:201], v[172:175], v[72:75]
	ds_read_b128 v[148:151], v246 offset:4096
	v_mfma_f32_16x16x32_bf16 v[76:79], v[202:205], v[168:171], v[76:79]
	ds_read_b128 v[152:155], v245 offset:6144
	v_mfma_f32_16x16x32_bf16 v[76:79], v[206:209], v[172:175], v[76:79]
	ds_read_b128 v[156:159], v246 offset:6144
	v_mfma_f32_16x16x32_bf16 v[80:83], v[194:197], v[176:179], v[80:83]
	v_mfma_f32_16x16x32_bf16 v[80:83], v[198:201], v[180:183], v[80:83]
	v_mfma_f32_16x16x32_bf16 v[84:87], v[202:205], v[176:179], v[84:87]
	v_mfma_f32_16x16x32_bf16 v[84:87], v[206:209], v[180:183], v[84:87]
	v_mfma_f32_16x16x32_bf16 v[88:91], v[194:197], v[186:189], v[88:91]
	v_mfma_f32_16x16x32_bf16 v[88:91], v[198:201], v[190:193], v[88:91]
	v_mfma_f32_16x16x32_bf16 v[92:95], v[202:205], v[186:189], v[92:95]
	v_mfma_f32_16x16x32_bf16 v[92:95], v[206:209], v[190:193], v[92:95]
	v_mfma_f32_16x16x32_bf16 v[96:99], v[210:213], v[160:163], v[96:99]
	ds_read_b128 v[194:197], v247 offset:0
	v_mfma_f32_16x16x32_bf16 v[96:99], v[214:217], v[164:167], v[96:99]
	ds_read_b128 v[198:201], v248 offset:0
	v_mfma_f32_16x16x32_bf16 v[100:103], v[218:221], v[160:163], v[100:103]
	ds_read_b128 v[202:205], v247 offset:2048
	v_mfma_f32_16x16x32_bf16 v[100:103], v[222:225], v[164:167], v[100:103]
	ds_read_b128 v[206:209], v248 offset:2048
	v_mfma_f32_16x16x32_bf16 v[104:107], v[210:213], v[168:171], v[104:107]
	s_add_i32 m0, s35, 0xc000
	v_mfma_f32_16x16x32_bf16 v[104:107], v[214:217], v[172:175], v[104:107]
	global_load_lds_dwordx4 v249, s[56:57]
	v_mfma_f32_16x16x32_bf16 v[108:111], v[218:221], v[168:171], v[108:111]
	s_add_i32 m0, s35, 0xe000
	v_mfma_f32_16x16x32_bf16 v[108:111], v[222:225], v[172:175], v[108:111]
	global_load_lds_dwordx4 v250, s[56:57]
	v_mfma_f32_16x16x32_bf16 v[112:115], v[210:213], v[176:179], v[112:115]
	s_add_i32 m0, s35, 0x18000
	v_mfma_f32_16x16x32_bf16 v[112:115], v[214:217], v[180:183], v[112:115]
	global_load_lds_dwordx4 v251, s[32:33]
	v_mfma_f32_16x16x32_bf16 v[116:119], v[218:221], v[176:179], v[116:119]
	s_add_i32 m0, s35, 0x1a000
	v_mfma_f32_16x16x32_bf16 v[116:119], v[222:225], v[180:183], v[116:119]
	global_load_lds_dwordx4 v252, s[32:33]
	v_mfma_f32_16x16x32_bf16 v[120:123], v[210:213], v[186:189], v[120:123]
	s_add_u32 s30, s30, s4
	s_addc_u32 s31, s31, s5
	v_mfma_f32_16x16x32_bf16 v[120:123], v[214:217], v[190:193], v[120:123]
	s_add_u32 s56, s56, s4
	s_addc_u32 s57, s57, s5
	v_mfma_f32_16x16x32_bf16 v[124:127], v[218:221], v[186:189], v[124:127]
	s_add_u32 s32, s32, s4
	s_addc_u32 s33, s33, s5
	v_mfma_f32_16x16x32_bf16 v[124:127], v[222:225], v[190:193], v[124:127]
	s_add_u32 s58, s58, s4
	s_addc_u32 s59, s59, s5
	s_add_i32 s34, s34, -1
	s_cmp_lg_u32 s34, 1
	s_cbranch_scc1 .Lp6_nosw1
	s_add_u32 s45, s16, 1
	s_and_b32 s40, s45, 1
	s_lshl_b32 s4, s40, 8
	s_sub_u32 s4, 128, s4
	s_sub_u32 s5, 0, s40
	s_mul_i32 s8, s40, 11136
	s_add_u32 s30, s26, s8
	s_addc_u32 s31, s27, 0
	s_add_u32 s32, s28, s8
	s_addc_u32 s33, s29, 0
	s_add_u32 s56, s30, 0x160000
	s_addc_u32 s57, s31, 0
	s_add_u32 s58, s32, 0x160000
	s_addc_u32 s59, s33, 0
